# v54 + removed the vmcnt(0) drain at each phase entry (nothing with a register result is outstanding there)
# baseline (speedup 1.0000x reference)
; __global__ void __launch_bounds__(512, 2) mega_fwd(Params P) {
;     ...
;         const int l = ph / NPH, k = ph - l * NPH;
;         const float* xcur = (l == 0 && k <= 2) ? P.in[0] : P.out;
;     ...
;         for (int rep = 0; rep < (((REP_MASK >> k) & 1) ? 2 : 1); ++rep)
;         switch (ONLY_K >= 0 ? ONLY_K : k) {
;         case 0: cvt_ffn(smem, ws, P.in[2] + (size_t)l * DM * NFF, P.in[3] + (size_t)l * DFF * DM); norm_rows(xcur, P.in[1] + l * DM, XN); break;
;         case 1: case 13: { EpiSwiGLU E{H}; run_gemm(smem, XN, WA, NFF, DM, E); } break;
;         case 2: { EpiResid E{xcur, P.out, 0.5f}; run_gemm(smem, H, WB, DM, DFF, E); } break;
;         case 3: cvt_mixer(smem, ws, P.in[5] + (size_t)l * DM * CIN_SRC, P.in[8] + (size_t)l * 2 * 64 * 512, P.in[10] + (size_t)l * 2 * 64 * 512, P.in[11] + (size_t)l * 128 * 512,
;                           P.in[21] + (size_t)l * 2 * 512 * DM, P.in[22] + (size_t)l * DM * DM);
;                 norm_rows(P.out, P.in[4] + l * DM, XN); break;
;         case 4: { EpiWin E{(bf16_t*)(ws + WS_PR), (bf16_t*)(ws + WS_QKV), (bf16_t*)(ws + WS_G)}; run_gemm(smem, XN, WA, NWIN, DM, E); } break;
;         case 5: prep_phase(P, l); break;
;         case 6: { EpiDecay E1{P.in[7] + l * 1024, (float*)(ws + WS_WF), (float*)(ws + WS_WBK)}; run_gemm(smem, (const bf16_t*)(ws + WS_LIN), (const bf16_t*)(ws + WS_WL), 1024, KLORA, E1);
;                   EpiIclr E2{P.in[9] + l * 1024, (bf16_t*)(ws + WS_AF), (bf16_t*)(ws + WS_AB), (bf16_t*)(ws + WS_GATE)}; run_gemm(smem, (const bf16_t*)(ws + WS_LIN), (const bf16_t*)(ws + WS_WL) + (size_t)1024 * KLORA, 1536, KLORA, E2); } break;
;         case 7: ck::chunk_pass<2>(smem, ws, P.in[13] + l * 512); break;
;         case 8: mixer_phase(P, l, smem); break;
;         case 9: outpost_phase(P, l, smem); break;
;         case 10: { EpiBranch E{(const bf16_t*)(ws + WS_G), XN}; run_gemm(smem, (const bf16_t*)(ws + WS_AO), (const bf16_t*)(ws + WS_WR), 2048, DM, E); } break;
;         case 11: { EpiResid E{P.out, P.out, 1.0f}; run_gemm(smem, XN, (const bf16_t*)(ws + WS_WO), DM, DM, E); } break;
;         case 12: norm_rows(P.out, P.in[23] + l * DM, XN); break;
;         case 14: { EpiResid E{P.out, P.out, 0.5f}; run_gemm(smem, H, WB, DM, DFF, E); } break;
.LBB0_18:
	s_xor_b64 s[0:1], s[0:1], -1
	v_writelane_b32 v254, s0, 57
	s_mov_b64 s[42:43], 0
	s_mov_b64 s[54:55], 0
	v_writelane_b32 v254, s1, 58
	s_mul_hi_i32 s0, s92, 0x88888889
	s_add_i32 s0, s0, s92
	s_lshr_b32 s1, s0, 31
	s_ashr_i32 s0, s0, 3
	s_add_i32 s2, s0, s1
	s_mul_i32 s0, s2, -15
	s_add_i32 s75, s0, s92
	s_lshl_b32 s0, s2, 10
	s_ashr_i32 s1, s0, 31
	v_writelane_b32 v254, s0, 59
	s_nop 1
	v_writelane_b32 v254, s1, 60
	s_lshl_b32 s0, s2, 6
	s_ashr_i32 s1, s0, 31
	v_writelane_b32 v254, s0, 61
	s_nop 1
	v_writelane_b32 v254, s1, 62
	s_mul_hi_i32 s0, s2, 0x1600000
	v_writelane_b32 v254, s0, 63
	s_mul_i32 s0, s2, 0x1600000
	v_writelane_b32 v255, s0, 0
	s_mul_hi_i32 s0, s2, 0xb00000
	v_writelane_b32 v255, s0, 1
	s_mul_i32 s0, s2, 0xb00000
	v_writelane_b32 v255, s0, 2
	s_mov_b32 s0, s2
	v_writelane_b32 v255, s0, 3
	s_nop 1
	v_writelane_b32 v255, s1, 4
	s_lshl_b32 s0, s2, 9
	s_ashr_i32 s1, s0, 31
	v_writelane_b32 v255, s0, 5
	s_cmp_lt_i32 s75, 7
	s_nop 0
	v_writelane_b32 v255, s1, 6
	s_mov_b64 s[0:1], -1
	v_writelane_b32 v255, s75, 7
	s_cbranch_scc1 .LBB0_423
	s_cmp_gt_i32 s75, 10
	s_cbranch_scc0 .LBB0_27
	s_cmp_gt_i32 s75, 12
	s_cbranch_scc0 .LBB0_45
	s_cmp_gt_i32 s75, 13
	s_mov_b64 s[2:3], -1
	s_cbranch_scc0 .LBB0_48
	s_cmp_eq_u32 s75, 14
	s_cbranch_scc0 .LBB0_47
	s_movk_i32 s6, 0xb00
	s_movk_i32 s0, 0x400
	s_ashr_i32 s1, s0, 31
	s_lshr_b32 s1, s1, 24
	s_add_i32 s0, s0, s1
	s_ashr_i32 s0, s0, 8
	s_mov_b32 s22, s24
	s_lshl_b32 s4, s0, 6
	v_mov_b32_e32 v12, v154
	s_cmp_ge_i32 s22, s4
	v_readfirstlane_b32 s5, v12
	s_cbranch_scc1 .LBB0_47
	v_lshlrev_b32_e32 v2, 4, v12
	v_add_u32_e32 v0, 0x2000, v2
	v_ashrrev_i32_e32 v1, 31, v0
	v_lshrrev_b32_e32 v1, 22, v1
	v_add_u32_e32 v1, v0, v1
	v_ashrrev_i32_e32 v1, 10, v1
	s_waitcnt lgkmcnt(0)
	v_mul_i32_i24_e32 v3, 0x400, v1
	v_sub_u32_e32 v0, v0, v3
	v_lshrrev_b32_e32 v3, 4, v0
	v_bitop3_b32 v3, v3, v0, 32 bitop3:0x6c
	v_ashrrev_i32_e32 v0, 31, v3
	v_lshrrev_b32_e32 v0, 26, v0
	v_add_u32_e32 v4, v3, v0
	v_lshlrev_b32_e32 v5, 3, v1
	v_ashrrev_i32_e32 v0, 6, v4
	v_and_b32_e32 v5, 0x7ffffff0, v5
	v_add_u32_e32 v5, v0, v5
	v_lshlrev_b32_e32 v0, 5, v1
	v_and_b32_e32 v0, 32, v0
	v_mad_u64_u32 v[0:1], s[14:15], v5, s6, v[0:1]
	v_and_b32_e32 v1, 0xc0, v4
	v_sub_u32_e32 v1, v3, v1
	v_ashrrev_i16_sdwa v1, v183, sext(v1) dst_sel:DWORD dst_unused:UNUSED_PAD src0_sel:DWORD src1_sel:BYTE_0
	v_bfe_i32 v1, v1, 0, 16
	v_add_lshl_u32 v130, v0, v1, 1
	v_bfe_i32 v0, v12, 27, 1
	v_lshrrev_b32_e32 v0, 22, v0
	v_add_u32_e32 v0, v2, v0
	v_and_b32_e32 v0, 0xfffffc00, v0
	v_sub_u32_e32 v0, v2, v0
	v_lshrrev_b32_e32 v1, 4, v0
	v_bitop3_b32 v2, v1, v0, 32 bitop3:0x6c
	v_ashrrev_i32_e32 v0, 31, v0
	v_lshrrev_b32_e32 v0, 26, v0
	v_add_u32_e32 v0, v2, v0
	v_ashrrev_i32_e32 v3, 6, v0
	v_ashrrev_i32_e32 v0, 31, v12
	v_lshrrev_b32_e32 v0, 26, v0
	v_add_u32_e32 v0, v12, v0
	v_ashrrev_i32_e32 v0, 6, v0
	v_lshlrev_b32_e32 v1, 3, v0
	v_and_b32_e32 v1, 0x7ffffff0, v1
	v_lshlrev_b32_e32 v0, 5, v0
	s_ashr_i32 s25, s22, 31
	v_add_u32_e32 v1, v3, v1
	v_and_b32_e32 v0, 32, v0
	s_lshr_b32 s1, s25, 29
	v_mad_u64_u32 v[0:1], s[14:15], v1, s6, v[0:1]
	s_add_i32 s1, s22, s1
	s_ashr_i32 s3, s5, 6
	s_ashr_i32 s7, s6, 31
	v_mul_i32_i24_e32 v1, 64, v3
	s_lshl_b32 s24, s0, 3
	s_ashr_i32 s2, s1, 3
	s_and_b32 s1, s1, -8
	s_ashr_i32 s12, s5, 8
	s_lshl_b64 s[8:9], s[6:7], 8
	s_lshl_b64 s[10:11], s[6:7], 9
	s_lshl_b32 s23, s3, 10
	v_sub_u32_e32 v1, v2, v1
	s_sub_i32 s1, s22, s1
	s_or_b32 s28, s24, 1
	v_ashrrev_i16_sdwa v1, v183, sext(v1) dst_sel:DWORD dst_unused:UNUSED_PAD src0_sel:DWORD src1_sel:BYTE_0
	s_cmp_lt_i32 s1, 0
	v_bfe_i32 v1, v1, 0, 16
	s_cselect_b32 s13, s28, s24
	s_abs_i32 s48, s24
	v_add_lshl_u32 v112, v0, v1, 1
	v_cvt_f32_u32_e32 v0, s48
	s_mul_i32 s1, s13, s1
	s_sub_i32 s13, 0, s48
	s_add_i32 s1, s1, s2
	v_rcp_iflag_f32_e32 v0, v0
	s_ashr_i32 s2, s1, 31
	s_bfe_i32 s29, s0, 0x1001c
	s_xor_b32 s0, s2, s29
	v_mul_f32_e32 v0, 0x4f7ffffe, v0
	v_cvt_u32_f32_e32 v0, v0
	s_abs_i32 s2, s1
	s_mov_b32 s38, s74
	v_mov_b32_e32 v131, v113
	v_readfirstlane_b32 s49, v0
	s_mul_i32 s13, s13, s49
	s_mul_hi_u32 s13, s49, s13
	s_add_i32 s49, s49, s13
	s_mul_hi_u32 s13, s2, s49
	s_mul_i32 s14, s13, s48
	s_sub_i32 s2, s2, s14
	s_add_i32 s14, s13, 1
	s_sub_i32 s15, s2, s48
	s_cmp_ge_u32 s2, s48
	s_cselect_b32 s13, s14, s13
	s_cselect_b32 s2, s15, s2
	s_add_i32 s14, s13, 1
	s_cmp_ge_u32 s2, s48
	s_cselect_b32 s2, s14, s13
	s_xor_b32 s2, s2, s0
	s_sub_i32 s0, s2, s0
	s_lshl_b32 s2, s0, 3
	s_sub_i32 s13, 64, s2
	s_min_i32 s13, s13, 8
	s_abs_i32 s15, s13
	v_cvt_f32_u32_e32 v0, s15
	s_sub_i32 s16, 0, s15
	s_mul_i32 s0, s0, s24
	s_sub_i32 s0, s1, s0
	v_rcp_iflag_f32_e32 v0, v0
	s_abs_i32 s14, s0
	s_xor_b32 s1, s0, s13
	s_ashr_i32 s1, s1, 31
	v_mul_f32_e32 v0, 0x4f7ffffe, v0
	v_cvt_u32_f32_e32 v0, v0
	s_mov_b64 s[40:41], s[64:65]
	v_readfirstlane_b32 s17, v0
	s_mul_i32 s16, s16, s17
	s_mul_hi_u32 s16, s17, s16
	s_add_i32 s17, s17, s16
	s_mul_hi_u32 s16, s14, s17
	s_mul_i32 s17, s16, s15
	s_sub_i32 s14, s14, s17
	s_add_i32 s17, s16, 1
	s_sub_i32 s18, s14, s15
	s_cmp_ge_u32 s14, s15
	s_cselect_b32 s16, s17, s16
	s_cselect_b32 s14, s18, s14
	s_add_i32 s17, s16, 1
	s_cmp_ge_u32 s14, s15
	s_cselect_b32 s14, s17, s16
	s_xor_b32 s14, s14, s1
	s_sub_i32 s71, s14, s1
	s_mul_i32 s1, s71, s13
	s_sub_i32 s0, s0, s1
	s_add_i32 s74, s0, s2
	s_ashr_i32 s0, s74, 31
	s_mul_i32 s0, s10, s0
	s_mul_hi_u32 s1, s10, s74
	s_add_i32 s2, s1, s0
	s_lshr_b64 s[0:1], s[6:7], 23
	s_mul_i32 s1, s0, s74
	s_add_i32 s2, s2, s1
	s_ashr_i32 s1, s71, 31
	s_mul_i32 s1, s10, s1
	s_mul_hi_u32 s14, s10, s71
	s_add_i32 s1, s14, s1
	s_mul_i32 s0, s0, s71
	s_add_i32 s1, s1, s0
	s_mul_i32 s0, s10, s71
	s_add_u32 s20, s56, s0
	s_addc_u32 s21, s57, s1
	s_add_i32 s50, s23, 0
	s_add_i32 m0, s50, 0x10000
	s_mul_i32 s13, s10, s74
	global_load_lds_dwordx4 v112, s[20:21]
	s_add_i32 m0, s50, 0x12000
	s_add_u32 s0, s20, s8
	global_load_lds_dwordx4 v130, s[20:21]
	s_addc_u32 s1, s21, s9
	s_add_i32 m0, s50, 0x14000
	v_lshl_add_u64 v[4:5], s[0:1], 0, v[112:113]
	global_load_lds_dwordx4 v112, s[0:1]
	s_add_i32 m0, s50, 0x16000
	v_lshl_add_u64 v[6:7], s[0:1], 0, v[130:131]
	global_load_lds_dwordx4 v130, s[0:1]
	v_readlane_b32 s0, v252, 4
	v_readlane_b32 s1, v252, 5
	s_add_u32 s18, s0, s13
	s_addc_u32 s19, s1, s2
	s_add_i32 s51, s50, 0x2000
	s_mov_b32 m0, s50
	s_add_u32 s0, s18, s8
	global_load_lds_dwordx4 v112, s[18:19]
	s_mov_b32 m0, s51
	s_addc_u32 s1, s19, s9
	s_add_i32 s54, s50, 0x4000
	global_load_lds_dwordx4 v130, s[18:19]
	s_mov_b32 m0, s54
	s_add_i32 s55, s50, 0x6000
	global_load_lds_dwordx4 v112, s[0:1]
	s_mov_b32 m0, s55
	s_cmp_eq_u32 s12, 1
	global_load_lds_dwordx4 v130, s[0:1]
	v_lshl_add_u64 v[0:1], s[20:21], 0, v[112:113]
	v_lshl_add_u64 v[2:3], s[20:21], 0, v[130:131]
	v_lshl_add_u64 v[8:9], s[18:19], 0, v[112:113]
	v_lshl_add_u64 v[10:11], s[18:19], 0, v[130:131]
	s_cselect_b64 s[0:1], -1, 0
	s_cmp_lg_u32 s12, 1
	s_cbranch_scc1 .LBB0_26
	s_barrier

; __device__ __forceinline__ int tid_opaque() { int t = (int)threadIdx.x; asm volatile("" : "+v"(t)); return t; }
; __device__ __forceinline__ int bid_opaque() { int t = (int)blockIdx.x; asm volatile("" : "+s"(t)); return t; }
; __device__ __forceinline__ float wave_sum(float v) { v += __shfl_xor(v, 32); v += __shfl_xor(v, 16); v += __shfl_xor(v, 8); v += __shfl_xor(v, 4); v += __shfl_xor(v, 2); v += __shfl_xor(v, 1); return v; }
; __device__ void norm_rows(const float* x, const float* g, bf16_t* xn) {
;     const int tid_ = tid_opaque(); const int lane = tid_ & 63, gw = bid_opaque() * 8 + (tid_ >> 6), nw = gridDim.x * 8;
;     f32x4 gv[4];
; #pragma unroll
;     for (int i = 0; i < 4; ++i) gv[i] = *(const f32x4*)(g + 4 * lane + 256 * i);
;     f32x4 nx[4];
; #pragma unroll
;     for (int i = 0; i < 4; ++i) nx[i] = (gw < T) ? *(const f32x4*)(x + (size_t)gw * DM + 4 * lane + 256 * i) : (f32x4){0.f, 0.f, 0.f, 0.f};
;     for (int row = gw; row < T; row += nw) {
;         f32x4 v[4]; float ss = 0.f;
; #pragma unroll
;         for (int i = 0; i < 4; ++i) { v[i] = nx[i]; ss += v[i][0] * v[i][0] + v[i][1] * v[i][1] + v[i][2] * v[i][2] + v[i][3] * v[i][3]; }
;         if (row + nw < T) {
; #pragma unroll
;             for (int i = 0; i < 4; ++i) nx[i] = *(const f32x4*)(x + (size_t)(row + nw) * DM + 4 * lane + 256 * i);
;         }
;         ss = wave_sum(ss); const float rs = rsqrtf(ss * (1.0f / 1024.0f) + 1e-6f);
.LBB0_49:
	v_writelane_b32 v255, s2, 8
	s_and_b64 vcc, exec, s[0:1]
	s_nop 0
	v_writelane_b32 v255, s3, 9
	s_cbranch_vccz .LBB0_79
	s_cmp_gt_i32 s75, 11
	s_mov_b64 s[0:1], -1
	s_cbranch_scc0 .LBB0_57
	v_mov_b32_e32 v34, v154
	s_mov_b32 s0, s24
	s_lshl_b32 s4, s0, 3
	v_ashrrev_i32_e32 v32, 6, v34
	v_add_u32_e32 v48, s4, v32
	s_movk_i32 s0, 0x4000
	v_cmp_gt_i32_e32 vcc, s0, v48
	s_and_saveexec_b64 s[0:1], vcc
	s_cbranch_execz .LBB0_56
	v_readlane_b32 s2, v254, 59
	v_readlane_b32 s3, v254, 60
	v_readlane_b32 s8, v252, 60
	v_ashrrev_i32_e32 v49, 31, v48
	s_lshl_b64 s[2:3], s[2:3], 2
	v_readlane_b32 s22, v253, 10
	v_lshlrev_b64 v[0:1], 12, v[48:49]
	v_lshlrev_b32_e32 v2, 4, v34
	v_readlane_b32 s23, v253, 11
	s_add_u32 s2, s22, s2
	v_lshl_add_u64 v[0:1], s[88:89], 0, v[0:1]
	v_and_b32_e32 v112, 0x3f0, v2
	s_addc_u32 s3, s23, s3
	v_lshl_add_u64 v[16:17], v[0:1], 0, v[112:113]
	s_waitcnt lgkmcnt(0)
	global_load_dwordx4 v[0:3], v112, s[2:3] offset:3072
	global_load_dwordx4 v[4:7], v112, s[2:3] offset:2048
	global_load_dwordx4 v[8:11], v112, s[2:3] offset:1024
	global_load_dwordx4 v[12:15], v112, s[2:3]
	global_load_dwordx4 v[28:31], v[16:17], off
	global_load_dwordx4 v[24:27], v[16:17], off offset:1024
	global_load_dwordx4 v[20:23], v[16:17], off offset:2048
	s_nop 0
	global_load_dwordx4 v[16:19], v[16:17], off offset:3072
	v_and_b32_e32 v35, 64, v185
	v_xor_b32_e32 v33, 32, v185
	v_add_u32_e32 v35, 64, v35
	v_cmp_lt_i32_e32 vcc, v33, v35
	s_ashr_i32 s5, s4, 31
	v_and_b32_e32 v34, 63, v34
	v_cndmask_b32_e32 v33, v185, v33, vcc
	v_lshlrev_b32_e32 v49, 2, v33
	v_xor_b32_e32 v33, 16, v185
	v_cmp_lt_i32_e32 vcc, v33, v35
	v_readlane_b32 s2, v254, 22
	v_readlane_b32 s3, v254, 23
	v_cndmask_b32_e32 v33, v185, v33, vcc
	v_lshlrev_b32_e32 v54, 2, v33
	v_xor_b32_e32 v33, 8, v185
	v_cmp_lt_i32_e32 vcc, v33, v35
	s_mov_b64 s[6:7], 0
	v_readlane_b32 s9, v252, 61
	v_cndmask_b32_e32 v33, v185, v33, vcc
	v_lshlrev_b32_e32 v55, 2, v33
	v_xor_b32_e32 v33, 4, v185
	v_cmp_lt_i32_e32 vcc, v33, v35
	v_readlane_b32 s10, v252, 62
	v_readlane_b32 s11, v252, 63
	v_cndmask_b32_e32 v33, v185, v33, vcc
	v_lshlrev_b32_e32 v56, 2, v33
	v_xor_b32_e32 v33, 2, v185
	v_cmp_lt_i32_e32 vcc, v33, v35
	v_readlane_b32 s12, v253, 0
	v_readlane_b32 s13, v253, 1
	v_cndmask_b32_e32 v33, v185, v33, vcc
	v_lshlrev_b32_e32 v57, 2, v33
	v_xor_b32_e32 v33, 1, v185
	v_cmp_lt_i32_e32 vcc, v33, v35
	v_readlane_b32 s14, v253, 2
	v_readlane_b32 s15, v253, 3
	v_cndmask_b32_e32 v33, v185, v33, vcc
	v_lshlrev_b32_e32 v58, 2, v33
	v_ashrrev_i32_e32 v33, 31, v32
	v_lshl_add_u64 v[36:37], v[32:33], 0, s[4:5]
	v_lshlrev_b64 v[36:37], 11, v[36:37]
	v_lshl_or_b32 v36, v34, 3, v36
	v_lshl_add_u64 v[50:51], s[2:3], 0, v[36:37]
	s_add_i32 s2, s4, s74
	v_add_u32_e32 v32, s2, v32
	v_ashrrev_i32_e32 v33, 31, v32
	v_lshlrev_b64 v[32:33], 12, v[32:33]
	v_readlane_b32 s2, v254, 26
	v_lshl_or_b32 v32, v34, 4, v32
	v_readlane_b32 s3, v254, 27
	v_readlane_b32 s16, v253, 4
	v_readlane_b32 s17, v253, 5
	v_lshl_add_u64 v[52:53], s[2:3], 0, v[32:33]
	v_readlane_b32 s18, v253, 6
	v_readlane_b32 s19, v253, 7
	v_readlane_b32 s20, v253, 8
	v_readlane_b32 s21, v253, 9
	s_waitcnt vmcnt(0)
	v_mov_b64_e32 v[34:35], v[30:31]
	v_mov_b64_e32 v[38:39], v[26:27]
	v_mov_b64_e32 v[42:43], v[22:23]
	v_mov_b64_e32 v[46:47], v[18:19]
	v_mov_b64_e32 v[32:33], v[28:29]
	v_mov_b64_e32 v[36:37], v[24:25]
	v_mov_b64_e32 v[40:41], v[20:21]
	v_mov_b64_e32 v[44:45], v[16:17]
	s_branch .LBB0_54

; __device__ __forceinline__ int tid_opaque() { int t = (int)threadIdx.x; asm volatile("" : "+v"(t)); return t; }
; #define PG8_WAIT_V(n) asm volatile("s_waitcnt vmcnt(" #n ")" ::: "memory")
; #define PG8_BAR __builtin_amdgcn_s_barrier()
; template <class Epi, class Sched, bool ALIGN_EPI = false, bool SP2 = false>
; __device__ __forceinline__ void gemm_phase(PG8_LAS unsigned char* lds, const Gemm g, const Sched& S, const Epi& E) {
;     const int tid = tid_opaque(), wid = __builtin_amdgcn_readfirstlane(tid >> 6), lane = tid & 63, wr = wid >> 2, wc = wid & 3, fr = lane & 15, fq = lane >> 4;
;     const int K = g.K, nt = K / BK;
;     unsigned voffA[2], voffB[2];
; #pragma unroll
;     for (int i = 0; i < 2; ++i) { int R, C; stage_rc(tid * 16 + i * 8192, R, C); const int Rb = Epi::PERM ? ((R & ~31) + perm32(R & 31)) : R;
;         voffA[i] = (unsigned)(R * K + C) * 2u; voffB[i] = (unsigned)(Rb * K + C) * 2u; }
;     const size_t kstep = (size_t)(BK * 2);
;     const size_t hstep = (size_t)HALF * K * 2;
;     const size_t tstep = 2 * hstep;
;     const unsigned ldsw = (unsigned)wid * 1024u;
;     const int aoff = lds_byte(wr * 64 + fr, fq * 8), boff = lds_byte(wc * 32 + fr, fq * 8);
;     ...
;     Unit cur, nxt; int ui = 0;
;     if (!S.next(0, cur)) return;
;     f32x4 acc[2][2][4][2];
; #pragma unroll
;     for (int a = 0; a < 2; ++a)
; #pragma unroll
;         for (int b = 0; b < 2; ++b)
; #pragma unroll
;             for (int m = 0; m < 4; ++m)
; #pragma unroll
;                 for (int n = 0; n < 2; ++n) acc[a][b][m][n] = (f32x4){0.f, 0.f, 0.f, 0.f};
;     bf16x8 At[4][2], B0[2][2], B1[2][2];
;     const char* cA = (const char*)g.A + (size_t)cur.pm * tstep; const char* cB = (const char*)g.Bt + (size_t)cur.pn * tstep;
;     S.a_ready(cur);
;     if constexpr (SP2) {
;         PG8_STAGE(PG8_SB(0, 0), cB, voffB); PG8_STAGE(PG8_SB(0, 1), cB + hstep, voffB); PG8_STAGE(PG8_SA(0, 0), cA, voffA); PG8_STAGE(PG8_SA(0, 1), cA + hstep, voffA);
;         if (wr == 1) PG8_BAR;
;         PG8_WAIT_V(2); PG8_BAR;
;         PG8_STAGE(PG8_SB(1, 0), cB + kstep, voffB); PG8_STAGE(PG8_SA(1, 0), cA + kstep, voffA); PG8_STAGE(PG8_SB(1, 1), cB + hstep + kstep, voffB);
;         PG8_WAIT_V(6); PG8_BAR;
;     } else {
;         PG8_STAGE(PG8_SB(0, 0), cB, voffB); PG8_STAGE(PG8_SA(0, 0), cA, voffA); PG8_STAGE(PG8_SB(0, 1), cB + hstep, voffB); PG8_STAGE(PG8_SA(0, 1), cA + hstep, voffA);
.LBB0_57:
	s_andn2_b64 vcc, exec, s[0:1]
	s_cbranch_vccnz .LBB0_79
	s_movk_i32 s4, 0x400
	s_movk_i32 s0, 0x400
	s_ashr_i32 s1, s0, 31
	s_lshr_b32 s1, s1, 24
	s_add_i32 s0, s0, s1
	s_ashr_i32 s0, s0, 8
	s_lshl_b32 s8, s0, 6
	v_mov_b32_e32 v12, v154
	s_cmp_ge_i32 s24, s8
	v_readfirstlane_b32 s6, v12
	s_cbranch_scc1 .LBB0_79
	v_lshlrev_b32_e32 v2, 4, v12
	v_add_u32_e32 v0, 0x2000, v2
	v_ashrrev_i32_e32 v1, 31, v0
	v_lshrrev_b32_e32 v1, 22, v1
	v_add_u32_e32 v1, v0, v1
	v_ashrrev_i32_e32 v1, 10, v1
	s_waitcnt lgkmcnt(0)
	v_mul_i32_i24_e32 v3, 0x400, v1
	v_sub_u32_e32 v0, v0, v3
	v_lshrrev_b32_e32 v3, 4, v0
	v_bitop3_b32 v3, v3, v0, 32 bitop3:0x6c
	v_ashrrev_i32_e32 v0, 31, v3
	v_lshrrev_b32_e32 v0, 26, v0
	v_add_u32_e32 v4, v3, v0
	v_lshlrev_b32_e32 v5, 3, v1
	v_ashrrev_i32_e32 v0, 6, v4
	v_and_b32_e32 v5, 0x7ffffff0, v5
	v_add_u32_e32 v5, v0, v5
	v_lshlrev_b32_e32 v0, 5, v1
	v_and_b32_e32 v0, 32, v0
	v_mad_u64_u32 v[0:1], s[2:3], v5, s4, v[0:1]
	v_and_b32_e32 v1, 0xc0, v4
	v_sub_u32_e32 v1, v3, v1
	v_ashrrev_i16_sdwa v1, v183, sext(v1) dst_sel:DWORD dst_unused:UNUSED_PAD src0_sel:DWORD src1_sel:BYTE_0
	v_bfe_i32 v1, v1, 0, 16
	v_add_lshl_u32 v130, v0, v1, 1
	v_bfe_i32 v0, v12, 27, 1
	v_lshrrev_b32_e32 v0, 22, v0
	v_add_u32_e32 v0, v2, v0
	v_and_b32_e32 v0, 0xfffffc00, v0
	v_sub_u32_e32 v0, v2, v0
	v_lshrrev_b32_e32 v1, 4, v0
	v_bitop3_b32 v2, v1, v0, 32 bitop3:0x6c
	v_ashrrev_i32_e32 v0, 31, v0
	v_lshrrev_b32_e32 v0, 26, v0
	v_add_u32_e32 v0, v2, v0
	v_ashrrev_i32_e32 v3, 6, v0
	v_ashrrev_i32_e32 v0, 31, v12
	v_lshrrev_b32_e32 v0, 26, v0
	v_add_u32_e32 v0, v12, v0
	v_ashrrev_i32_e32 v0, 6, v0
	v_lshlrev_b32_e32 v1, 3, v0
	v_and_b32_e32 v1, 0x7ffffff0, v1
	v_lshlrev_b32_e32 v0, 5, v0
	s_ashr_i32 s29, s24, 31
	v_add_u32_e32 v1, v3, v1
	v_and_b32_e32 v0, 32, v0
	s_lshr_b32 s1, s29, 29
	v_mad_u64_u32 v[0:1], s[2:3], v1, s4, v[0:1]
	s_add_i32 s1, s24, s1
	s_ashr_i32 s7, s6, 6
	s_ashr_i32 s5, s4, 31
	s_lshl_b32 s28, s0, 3
	s_ashr_i32 s2, s1, 3
	s_and_b32 s1, s1, -8
	s_ashr_i32 s9, s6, 8
	s_lshl_b64 s[10:11], s[4:5], 8
	s_lshl_b64 s[12:13], s[4:5], 9
	s_lshl_b32 s25, s7, 10
	s_sub_i32 s1, s24, s1
	s_or_b32 s48, s28, 1
	s_cmp_lt_i32 s1, 0
	s_cselect_b32 s3, s48, s28
	v_mul_i32_i24_e32 v1, 64, v3
	s_mul_i32 s1, s3, s1
	v_sub_u32_e32 v1, v2, v1
	s_add_i32 s1, s1, s2
	v_ashrrev_i16_sdwa v1, v183, sext(v1) dst_sel:DWORD dst_unused:UNUSED_PAD src0_sel:DWORD src1_sel:BYTE_0
	s_ashr_i32 s2, s1, 31
	s_bfe_i32 s49, s0, 0x1001c
	v_bfe_i32 v1, v1, 0, 16
	s_xor_b32 s0, s2, s49
	s_abs_i32 s2, s28
	v_add_lshl_u32 v112, v0, v1, 1
	v_cvt_f32_u32_e32 v0, s2
	s_sub_i32 s3, 0, s2
	s_abs_i32 s14, s1
	v_mov_b32_e32 v131, v113
	v_rcp_iflag_f32_e32 v0, v0
	s_mov_b64 s[40:41], s[64:65]
	v_mul_f32_e32 v0, 0x4f7ffffe, v0
	v_cvt_u32_f32_e32 v0, v0
	s_nop 0
	v_readfirstlane_b32 s15, v0
	s_mul_i32 s3, s3, s15
	s_mul_hi_u32 s3, s15, s3
	s_add_i32 s3, s15, s3
	s_mul_hi_u32 s15, s14, s3
	s_mul_i32 s16, s15, s2
	s_sub_i32 s14, s14, s16
	s_add_i32 s16, s15, 1
	s_sub_i32 s17, s14, s2
	s_cmp_ge_u32 s14, s2
	s_cselect_b32 s15, s16, s15
	s_cselect_b32 s14, s17, s14
	s_add_i32 s16, s15, 1
	s_cmp_ge_u32 s14, s2
	s_cselect_b32 s14, s16, s15
	s_xor_b32 s14, s14, s0
	s_sub_i32 s0, s14, s0
	s_lshl_b32 s14, s0, 3
	s_sub_i32 s15, 64, s14
	s_min_i32 s15, s15, 8
	s_abs_i32 s17, s15
	v_cvt_f32_u32_e32 v0, s17
	s_sub_i32 s18, 0, s17
	s_mul_i32 s0, s0, s28
	s_sub_i32 s0, s1, s0
	v_rcp_iflag_f32_e32 v0, v0
	s_abs_i32 s16, s0
	s_xor_b32 s1, s0, s15
	s_ashr_i32 s1, s1, 31
	v_mul_f32_e32 v0, 0x4f7ffffe, v0
	v_cvt_u32_f32_e32 v0, v0
	s_nop 0
	v_readfirstlane_b32 s19, v0
	s_mul_i32 s18, s18, s19
	s_mul_hi_u32 s18, s19, s18
	s_add_i32 s19, s19, s18
	s_mul_hi_u32 s18, s16, s19
	s_mul_i32 s19, s18, s17
	s_sub_i32 s16, s16, s19
	s_add_i32 s19, s18, 1
	s_sub_i32 s20, s16, s17
	s_cmp_ge_u32 s16, s17
	s_cselect_b32 s18, s19, s18
	s_cselect_b32 s16, s20, s16
	s_add_i32 s19, s18, 1
	s_cmp_ge_u32 s16, s17
	s_cselect_b32 s16, s19, s18
	s_xor_b32 s16, s16, s1
	s_sub_i32 s75, s16, s1
	s_mul_i32 s1, s75, s15
	s_sub_i32 s0, s0, s1
	s_add_i32 s77, s0, s14
	s_ashr_i32 s0, s77, 31
	s_mul_i32 s0, s12, s0
	s_mul_hi_u32 s1, s12, s77
	s_add_i32 s14, s1, s0
	s_lshr_b64 s[0:1], s[4:5], 23
	s_mul_i32 s1, s0, s77
	s_add_i32 s14, s14, s1
	s_ashr_i32 s1, s75, 31
	s_mul_i32 s1, s12, s1
	s_mul_hi_u32 s16, s12, s75
	s_add_i32 s1, s16, s1
	s_mul_i32 s0, s0, s75
	s_add_i32 s1, s1, s0
	s_mul_i32 s0, s12, s75
	v_readlane_b32 s16, v252, 6
	v_readlane_b32 s17, v252, 7
	s_add_u32 s22, s16, s0
	s_addc_u32 s23, s17, s1
	s_add_i32 s50, s25, 0
	s_add_i32 m0, s50, 0x10000
	s_mul_i32 s15, s12, s77
	global_load_lds_dwordx4 v112, s[22:23]
	s_add_i32 m0, s50, 0x12000
	s_add_u32 s0, s22, s10
	global_load_lds_dwordx4 v130, s[22:23]
	s_addc_u32 s1, s23, s11
	s_add_i32 m0, s50, 0x14000
	v_lshl_add_u64 v[4:5], s[0:1], 0, v[112:113]
	global_load_lds_dwordx4 v112, s[0:1]
	s_add_i32 m0, s50, 0x16000
	s_add_u32 s20, s96, s15
	s_addc_u32 s21, s97, s14
	s_add_i32 s51, s50, 0x2000
	v_lshl_add_u64 v[6:7], s[0:1], 0, v[130:131]
	global_load_lds_dwordx4 v130, s[0:1]
	s_mov_b32 m0, s50
	s_add_u32 s0, s20, s10
	global_load_lds_dwordx4 v112, s[20:21]
	s_mov_b32 m0, s51
	s_addc_u32 s1, s21, s11
	s_add_i32 s54, s50, 0x4000
	global_load_lds_dwordx4 v130, s[20:21]
	s_mov_b32 m0, s54
	s_add_i32 s55, s50, 0x6000
	global_load_lds_dwordx4 v112, s[0:1]
	s_mov_b32 m0, s55
	s_cmp_eq_u32 s9, 1
	global_load_lds_dwordx4 v130, s[0:1]
	v_lshl_add_u64 v[0:1], s[22:23], 0, v[112:113]
	v_lshl_add_u64 v[2:3], s[22:23], 0, v[130:131]
	v_lshl_add_u64 v[8:9], s[20:21], 0, v[112:113]
	v_lshl_add_u64 v[10:11], s[20:21], 0, v[130:131]
	s_cselect_b64 s[0:1], -1, 0
	s_cmp_lg_u32 s9, 1
	s_cbranch_scc1 .LBB0_61
	s_barrier

; __device__ __forceinline__ int bid_opaque() { int t = (int)blockIdx.x; asm volatile("" : "+s"(t)); return t; }
; #define PG8_LAS __attribute__((address_space(3)))
; template <class Epi> __device__ __forceinline__ void run_gemm(unsigned char* smem, const bf16_t* A, const bf16_t* Bt, int N, int K, const Epi& E) {
;     asm volatile("" : "+s"(K)); asm volatile("" : "+s"(N));
;     pg8::Gemm g{A, Bt, T, N, K}; pg8::StaticOrder S; S.init(T, N, (int)gridDim.x, bid_opaque());
;     pg8::gemm_phase<Epi, pg8::StaticOrder, true, true>((PG8_LAS unsigned char*)smem, g, S, E);
; __global__ void __launch_bounds__(512, 2) mega_fwd(Params P) {
;     ...
;         switch (ONLY_K >= 0 ? ONLY_K : k) {
;         case 0: cvt_ffn(smem, ws, P.in[2] + (size_t)l * DM * NFF, P.in[3] + (size_t)l * DFF * DM); norm_rows(xcur, P.in[1] + l * DM, XN); break;
;         case 1: case 13: { EpiSwiGLU E{H}; run_gemm(smem, XN, WA, NFF, DM, E); } break;
;         case 2: { EpiResid E{xcur, P.out, 0.5f}; run_gemm(smem, H, WB, DM, DFF, E); } break;
;         case 3: cvt_mixer(smem, ws, P.in[5] + (size_t)l * DM * CIN_SRC, P.in[8] + (size_t)l * 2 * 64 * 512, P.in[10] + (size_t)l * 2 * 64 * 512, P.in[11] + (size_t)l * 128 * 512,
;                           P.in[21] + (size_t)l * 2 * 512 * DM, P.in[22] + (size_t)l * DM * DM);
;                 norm_rows(P.out, P.in[4] + l * DM, XN); break;
;         case 4: { EpiWin E{(bf16_t*)(ws + WS_PR), (bf16_t*)(ws + WS_QKV), (bf16_t*)(ws + WS_G)}; run_gemm(smem, XN, WA, NWIN, DM, E); } break;
;         case 5: prep_phase(P, l); break;
;         case 6: { EpiDecay E1{P.in[7] + l * 1024, (float*)(ws + WS_WF), (float*)(ws + WS_WBK)}; run_gemm(smem, (const bf16_t*)(ws + WS_LIN), (const bf16_t*)(ws + WS_WL), 1024, KLORA, E1);
;                   EpiIclr E2{P.in[9] + l * 1024, (bf16_t*)(ws + WS_AF), (bf16_t*)(ws + WS_AB), (bf16_t*)(ws + WS_GATE)}; run_gemm(smem, (const bf16_t*)(ws + WS_LIN), (const bf16_t*)(ws + WS_WL) + (size_t)1024 * KLORA, 1536, KLORA, E2); } break;
;         case 7: ck::chunk_pass<2>(smem, ws, P.in[13] + l * 512); break;
;         case 8: mixer_phase(P, l, smem); break;
;         case 9: outpost_phase(P, l, smem); break;
;         case 10: { EpiBranch E{(const bf16_t*)(ws + WS_G), XN}; run_gemm(smem, (const bf16_t*)(ws + WS_AO), (const bf16_t*)(ws + WS_WR), 2048, DM, E); } break;
.LBB0_80:
	v_readlane_b32 s0, v255, 5
	v_readlane_b32 s1, v255, 6
	s_lshl_b64 s[36:37], s[0:1], 2
	v_readlane_b32 s0, v252, 40
	v_readlane_b32 s10, v252, 50
	v_readlane_b32 s1, v252, 41
	v_readlane_b32 s11, v252, 51
	s_add_u32 s0, s10, s36
	s_addc_u32 s1, s11, s37
	v_writelane_b32 v255, s0, 10
	v_readlane_b32 s2, v252, 42
	v_readlane_b32 s3, v252, 43
	v_writelane_b32 v255, s1, 11
	s_mov_b64 s[0:1], -1
	v_readlane_b32 s2, v255, 7
	s_cmp_lt_i32 s2, 9
	v_readlane_b32 s4, v252, 44
	v_readlane_b32 s5, v252, 45
	v_readlane_b32 s6, v252, 46
	v_readlane_b32 s7, v252, 47
	v_readlane_b32 s8, v252, 48
	v_readlane_b32 s9, v252, 49
	v_readlane_b32 s12, v252, 52
	v_readlane_b32 s13, v252, 53
	v_readlane_b32 s14, v252, 54
	v_readlane_b32 s15, v252, 55
	s_cbranch_scc1 .LBB0_113
	s_cmp_gt_i32 s2, 9
	v_readlane_b32 s6, v254, 50
	s_cbranch_scc0 .LBB0_104
	s_movk_i32 s0, 0x400
	s_movk_i32 s1, 0x800
	s_ashr_i32 s2, s1, 31
	s_lshr_b32 s2, s2, 24
	s_add_i32 s1, s1, s2
	s_ashr_i32 s2, s1, 8
	s_mov_b32 s48, s6
	s_lshl_b32 s10, s2, 6
	v_mov_b32_e32 v18, v154
	s_cmp_ge_i32 s48, s10
	v_readfirstlane_b32 s4, v18
	s_cbranch_scc1 .LBB0_103
; __device__ __forceinline__ int tid_opaque() { int t = (int)threadIdx.x; asm volatile("" : "+v"(t)); return t; }
; #define PG8_WAIT_V(n) asm volatile("s_waitcnt vmcnt(" #n ")" ::: "memory")
; #define PG8_BAR __builtin_amdgcn_s_barrier()
; template <class Epi, class Sched, bool ALIGN_EPI = false, bool SP2 = false>
; __device__ __forceinline__ void gemm_phase(PG8_LAS unsigned char* lds, const Gemm g, const Sched& S, const Epi& E) {
;     const int tid = tid_opaque(), wid = __builtin_amdgcn_readfirstlane(tid >> 6), lane = tid & 63, wr = wid >> 2, wc = wid & 3, fr = lane & 15, fq = lane >> 4;
;     const int K = g.K, nt = K / BK;
;     unsigned voffA[2], voffB[2];
; #pragma unroll
;     for (int i = 0; i < 2; ++i) { int R, C; stage_rc(tid * 16 + i * 8192, R, C); const int Rb = Epi::PERM ? ((R & ~31) + perm32(R & 31)) : R;
;         voffA[i] = (unsigned)(R * K + C) * 2u; voffB[i] = (unsigned)(Rb * K + C) * 2u; }
;     const size_t kstep = (size_t)(BK * 2);
;     const size_t hstep = (size_t)HALF * K * 2;
;     const size_t tstep = 2 * hstep;
;     const unsigned ldsw = (unsigned)wid * 1024u;
;     const int aoff = lds_byte(wr * 64 + fr, fq * 8), boff = lds_byte(wc * 32 + fr, fq * 8);
;     ...
;     Unit cur, nxt; int ui = 0;
;     if (!S.next(0, cur)) return;
;     f32x4 acc[2][2][4][2];
; #pragma unroll
;     for (int a = 0; a < 2; ++a)
; #pragma unroll
;         for (int b = 0; b < 2; ++b)
; #pragma unroll
;             for (int m = 0; m < 4; ++m)
; #pragma unroll
;                 for (int n = 0; n < 2; ++n) acc[a][b][m][n] = (f32x4){0.f, 0.f, 0.f, 0.f};
;     bf16x8 At[4][2], B0[2][2], B1[2][2];
;     const char* cA = (const char*)g.A + (size_t)cur.pm * tstep; const char* cB = (const char*)g.Bt + (size_t)cur.pn * tstep;
;     S.a_ready(cur);
;     if constexpr (SP2) {
;         PG8_STAGE(PG8_SB(0, 0), cB, voffB); PG8_STAGE(PG8_SB(0, 1), cB + hstep, voffB); PG8_STAGE(PG8_SA(0, 0), cA, voffA); PG8_STAGE(PG8_SA(0, 1), cA + hstep, voffA);
;         if (wr == 1) PG8_BAR;
;         PG8_WAIT_V(2); PG8_BAR;
;         PG8_STAGE(PG8_SB(1, 0), cB + kstep, voffB); PG8_STAGE(PG8_SA(1, 0), cA + kstep, voffA); PG8_STAGE(PG8_SB(1, 1), cB + hstep + kstep, voffB);
;         PG8_WAIT_V(6); PG8_BAR;
;     } else {
;         PG8_STAGE(PG8_SB(0, 0), cB, voffB); PG8_STAGE(PG8_SA(0, 0), cA, voffA); PG8_STAGE(PG8_SB(0, 1), cB + hstep, voffB); PG8_STAGE(PG8_SA(0, 1), cA + hstep, voffA);
	v_lshlrev_b32_e32 v0, 4, v18
	v_add_u32_e32 v1, 0x2000, v0
	v_ashrrev_i32_e32 v2, 31, v1
	v_lshrrev_b32_e32 v2, 22, v2
	v_add_u32_e32 v2, v1, v2
	v_ashrrev_i32_e32 v2, 10, v2
	s_waitcnt lgkmcnt(0)
	v_mul_i32_i24_e32 v3, 0x400, v2
	v_sub_u32_e32 v1, v1, v3
	v_lshrrev_b32_e32 v3, 4, v1
	v_bitop3_b32 v1, v3, v1, 32 bitop3:0x6c
	v_ashrrev_i32_e32 v3, 31, v1
	v_lshrrev_b32_e32 v3, 26, v3
	v_add_u32_e32 v3, v1, v3
	v_lshlrev_b32_e32 v5, 3, v2
	v_ashrrev_i32_e32 v4, 6, v3
	v_and_b32_e32 v5, -16, v5
	v_lshlrev_b32_e32 v2, 5, v2
	v_add_u32_e32 v5, v4, v5
	v_and_b32_e32 v12, 32, v2
	v_and_b32_e32 v2, 0xc0, v3
	v_and_b32_e32 v4, 3, v4
	s_mov_b32 s3, 0x7fffffe0
	v_lshrrev_b32_e32 v6, 2, v5
	v_lshlrev_b32_e32 v7, 1, v5
	v_sub_u32_e32 v1, v1, v2
	v_and_or_b32 v4, v5, s3, v4
	v_and_b32_e32 v6, 4, v6
	v_and_b32_e32 v7, 24, v7
	v_ashrrev_i16_sdwa v1, v183, sext(v1) dst_sel:DWORD dst_unused:UNUSED_PAD src0_sel:DWORD src1_sel:BYTE_0
	v_or3_b32 v4, v4, v6, v7
	v_bfe_i32 v13, v1, 0, 16
	v_mul_lo_u32 v4, v4, s0
	v_add_u32_e32 v1, v12, v13
	v_mul_lo_u32 v14, v5, s0
	v_add_lshl_u32 v130, v4, v1, 1
	v_add_lshl_u32 v132, v1, v14, 1
	v_bfe_i32 v1, v18, 27, 1
	v_lshrrev_b32_e32 v1, 22, v1
	v_add_u32_e32 v1, v0, v1
	v_and_b32_e32 v1, 0xfffffc00, v1
	v_sub_u32_e32 v0, v0, v1
	v_ashrrev_i32_e32 v2, 31, v18
	v_lshrrev_b32_e32 v1, 4, v0
	v_lshrrev_b32_e32 v2, 26, v2
	v_bitop3_b32 v1, v1, v0, 32 bitop3:0x6c
	v_ashrrev_i32_e32 v0, 31, v0
	v_add_u32_e32 v2, v18, v2
	v_lshrrev_b32_e32 v0, 26, v0
	v_ashrrev_i32_e32 v2, 6, v2
	v_add_u32_e32 v0, v1, v0
	v_lshlrev_b32_e32 v3, 3, v2
	v_ashrrev_i32_e32 v0, 6, v0
	v_and_b32_e32 v3, -16, v3
	v_add_u32_e32 v3, v0, v3
	v_and_b32_e32 v4, 3, v0
	s_ashr_i32 s51, s48, 31
	v_and_or_b32 v4, v3, s3, v4
	s_lshr_b32 s3, s51, 29
	v_mul_i32_i24_e32 v0, 64, v0
	s_add_i32 s3, s48, s3
	s_ashr_i32 s5, s4, 6
	s_ashr_i32 s1, s0, 31
	v_lshrrev_b32_e32 v5, 2, v3
	v_lshlrev_b32_e32 v6, 1, v3
	v_sub_u32_e32 v0, v1, v0
	s_lshl_b32 s50, s2, 3
	s_ashr_i32 s7, s3, 3
	s_and_b32 s3, s3, -8
	s_ashr_i32 s6, s4, 8
	s_lshl_b64 s[12:13], s[0:1], 8
	s_lshl_b64 s[14:15], s[0:1], 9
	s_lshl_b32 s49, s5, 10
	v_and_b32_e32 v5, 4, v5
	v_and_b32_e32 v6, 24, v6
	v_lshlrev_b32_e32 v2, 5, v2
	v_ashrrev_i16_sdwa v0, v183, sext(v0) dst_sel:DWORD dst_unused:UNUSED_PAD src0_sel:DWORD src1_sel:BYTE_0
	s_sub_i32 s3, s48, s3
	s_or_b32 s40, s50, 1
	v_or3_b32 v4, v4, v5, v6
	v_and_b32_e32 v15, 32, v2
	v_bfe_i32 v16, v0, 0, 16
	s_cmp_lt_i32 s3, 0
	s_mov_b64 s[38:39], s[64:65]
	v_mul_lo_u32 v4, v4, s0
	v_add_u32_e32 v0, v15, v16
	v_mul_lo_u32 v17, v3, s0
	s_cselect_b32 s11, s40, s50
	s_abs_i32 s64, s50
	v_add_lshl_u32 v112, v4, v0, 1
	v_add_lshl_u32 v134, v0, v17, 1
	v_cvt_f32_u32_e32 v0, s64
	s_mul_i32 s3, s11, s3
	s_sub_i32 s11, 0, s64
	s_add_i32 s3, s3, s7
	v_rcp_iflag_f32_e32 v0, v0
	s_ashr_i32 s7, s3, 31
	s_bfe_i32 s41, s2, 0x1001c
	s_xor_b32 s2, s7, s41
	v_mul_f32_e32 v0, 0x4f7ffffe, v0
	v_cvt_u32_f32_e32 v0, v0
	s_abs_i32 s7, s3
	v_readlane_b32 s8, v252, 10
	v_readlane_b32 s9, v252, 11
	v_readfirstlane_b32 s65, v0
	s_mul_i32 s11, s11, s65
	s_mul_hi_u32 s11, s65, s11
	s_add_i32 s65, s65, s11
	s_mul_hi_u32 s11, s7, s65
	s_mul_i32 s16, s11, s64
	s_sub_i32 s7, s7, s16
	s_add_i32 s16, s11, 1
	s_sub_i32 s17, s7, s64
	s_cmp_ge_u32 s7, s64
	s_cselect_b32 s11, s16, s11
	s_cselect_b32 s7, s17, s7
	s_add_i32 s16, s11, 1
	s_cmp_ge_u32 s7, s64
	s_cselect_b32 s7, s16, s11
	s_xor_b32 s7, s7, s2
	s_sub_i32 s2, s7, s2
	s_lshl_b32 s7, s2, 3
	s_sub_i32 s11, 64, s7
	s_min_i32 s11, s11, 8
	s_abs_i32 s17, s11
	v_cvt_f32_u32_e32 v0, s17
	s_sub_i32 s18, 0, s17
	s_mul_i32 s2, s2, s50
	s_sub_i32 s3, s3, s2
	v_rcp_iflag_f32_e32 v0, v0
	s_abs_i32 s16, s3
	s_xor_b32 s2, s3, s11
	s_ashr_i32 s2, s2, 31
	v_mul_f32_e32 v0, 0x4f7ffffe, v0
	v_cvt_u32_f32_e32 v0, v0
	v_mov_b32_e32 v131, v113
	v_mov_b32_e32 v135, v113
	v_mov_b32_e32 v133, v113
	v_readfirstlane_b32 s19, v0
	s_mul_i32 s18, s18, s19
	s_mul_hi_u32 s18, s19, s18
	s_add_i32 s19, s19, s18
	s_mul_hi_u32 s18, s16, s19
	s_mul_i32 s19, s18, s17
	s_sub_i32 s16, s16, s19
	s_add_i32 s19, s18, 1
	s_sub_i32 s20, s16, s17
	s_cmp_ge_u32 s16, s17
	s_cselect_b32 s18, s19, s18
	s_cselect_b32 s16, s20, s16
	s_add_i32 s19, s18, 1
	s_cmp_ge_u32 s16, s17
	s_cselect_b32 s16, s19, s18
	s_xor_b32 s16, s16, s2
	s_sub_i32 s2, s16, s2
	s_mul_i32 s11, s2, s11
	s_sub_i32 s3, s3, s11
	s_add_i32 s3, s3, s7
	s_lshr_b64 s[16:17], s[0:1], 23
	s_ashr_i32 s7, s3, 31
	s_ashr_i32 s17, s2, 31
	s_mul_i32 s7, s14, s7
	s_mul_hi_u32 s11, s14, s3
	s_mul_i32 s17, s14, s17
	s_mul_hi_u32 s18, s14, s2
	s_add_i32 s7, s11, s7
	s_mul_i32 s11, s16, s3
	s_add_i32 s17, s18, s17
	s_mul_i32 s16, s16, s2
	s_add_i32 s7, s7, s11
	s_add_i32 s17, s17, s16
	s_mul_i32 s16, s14, s2
	s_add_u32 s24, s8, s16
	s_addc_u32 s25, s9, s17
	s_add_i32 s70, s49, 0
	s_add_i32 m0, s70, 0x10000
	s_mul_i32 s11, s14, s3
	global_load_lds_dwordx4 v112, s[24:25]
	s_add_i32 m0, s70, 0x12000
	s_add_u32 s16, s24, s12
	global_load_lds_dwordx4 v130, s[24:25]
	s_addc_u32 s17, s25, s13
	s_add_i32 m0, s70, 0x14000
	v_readlane_b32 s8, v252, 4
	global_load_lds_dwordx4 v112, s[16:17]
	s_add_i32 m0, s70, 0x16000
	v_readlane_b32 s9, v252, 5
	s_add_u32 s28, s8, s11
	s_addc_u32 s29, s9, s7
	s_add_i32 s71, s70, 0x2000
	v_lshl_add_u64 v[4:5], s[16:17], 0, v[112:113]
	v_lshl_add_u64 v[6:7], s[16:17], 0, v[130:131]
	global_load_lds_dwordx4 v130, s[16:17]
	s_mov_b32 m0, s70
	s_add_u32 s16, s28, s12
	global_load_lds_dwordx4 v134, s[28:29]
	s_mov_b32 m0, s71
	s_addc_u32 s17, s29, s13
	s_add_i32 s77, s70, 0x4000
	global_load_lds_dwordx4 v132, s[28:29]
	s_mov_b32 m0, s77
	s_add_i32 s79, s70, 0x6000
	global_load_lds_dwordx4 v134, s[16:17]
	s_mov_b32 m0, s79
	s_cmp_eq_u32 s6, 1
	global_load_lds_dwordx4 v132, s[16:17]
	v_lshl_add_u64 v[0:1], s[24:25], 0, v[112:113]
	v_lshl_add_u64 v[2:3], s[24:25], 0, v[130:131]
	v_lshl_add_u64 v[8:9], s[28:29], 0, v[134:135]
	v_lshl_add_u64 v[10:11], s[28:29], 0, v[132:133]
	s_cselect_b64 s[42:43], -1, 0
	s_cmp_lg_u32 s6, 1
	s_cbranch_scc1 .LBB0_85
	s_barrier

; __device__ __forceinline__ int tid_opaque() { int t = (int)threadIdx.x; asm volatile("" : "+v"(t)); return t; }
; __device__ __forceinline__ float wave_sum(float v) { v += __shfl_xor(v, 32); v += __shfl_xor(v, 16); v += __shfl_xor(v, 8); v += __shfl_xor(v, 4); v += __shfl_xor(v, 2); v += __shfl_xor(v, 1); return v; }
; __device__ void outpost_phase(const Params& P, int l, unsigned char* smem) {
;     unsigned char* ws = P.ws;
;     const bf16_t* YF = (const bf16_t*)(ws + WS_YF); const bf16_t* YB = (const bf16_t*)(ws + WS_YB); const bf16_t* R = (const bf16_t*)(ws + WS_R); const bf16_t* V = (const bf16_t*)(ws + WS_V);
;     const bf16_t* AF = (const bf16_t*)(ws + WS_AF); const bf16_t* AB = (const bf16_t*)(ws + WS_AB); const bf16_t* Kb = (const bf16_t*)(ws + WS_K); const float* k_a = P.in[13] + l * 512; const bf16_t* GATE = (const bf16_t*)(ws + WS_GATE);
;     const bf16_t* O0 = (const bf16_t*)(ws + WS_O0); const bf16_t* O1 = (const bf16_t*)(ws + WS_O1); bf16_t* AO = (bf16_t*)(ws + WS_AO);
;     const float* r_k = P.in[14] + l * 512; const float* lng = P.in[15] + l * 512; const float* lnb = P.in[16] + l * 512; const float* lamv = P.in[19] + l * 256; const float* subg = P.in[20] + l * 128;
;     const int tid_ = tid_opaque(); const int lane = tid_ & 63, w = __builtin_amdgcn_readfirstlane(tid_ >> 6), hi = lane >> 5, l32 = lane & 31;
;     float* Yb = (float*)smem;
;     const float lam_init = 0.8f - 0.6f * expf(-0.3f * (float)l);
;     const float s1 = wave_sum(lamv[lane] * lamv[64 + lane]), s2 = wave_sum(lamv[128 + lane] * lamv[192 + lane]);
;     const float lam = expf(s1) - expf(s2) + lam_init;
;     const int c0 = 8 * lane;
;     const f32x4 ka0 = *(const f32x4*)(k_a + c0), ka1 = *(const f32x4*)(k_a + c0 + 4); const f32x4 rk0 = *(const f32x4*)(r_k + c0), rk1 = *(const f32x4*)(r_k + c0 + 4), lg0 = *(const f32x4*)(lng + c0), lg1 = *(const f32x4*)(lng + c0 + 4), lb0 = *(const f32x4*)(lnb + c0), lb1 = *(const f32x4*)(lnb + c0 + 4);
;     const f32x4 sg0 = *(const f32x4*)(subg + (c0 & 127)), sg1 = *(const f32x4*)(subg + (c0 & 127) + 4);
.LBB0_104:
	s_andn2_b64 vcc, exec, s[0:1]
	s_cbranch_vccnz .LBB0_112
	v_readlane_b32 s0, v255, 3
	v_readlane_b32 s1, v255, 4
	s_mov_b32 s2, s0
	s_lshl_b32 s0, s0, 7
	s_ashr_i32 s1, s0, 31
	v_readlane_b32 s8, v252, 60
	s_lshl_b64 s[0:1], s[0:1], 2
	v_readlane_b32 s16, v253, 4
	v_readlane_b32 s17, v253, 5
	s_add_u32 s0, s16, s0
	s_addc_u32 s1, s17, s1
	s_lshl_b32 s2, s2, 8
	s_ashr_i32 s3, s2, 31
	v_readlane_b32 s14, v253, 2
	s_lshl_b64 s[2:3], s[2:3], 2
	v_mov_b32_e32 v1, v154
	v_readlane_b32 s15, v253, 3
	s_add_u32 s4, s14, s2
	s_addc_u32 s5, s15, s3
	v_and_b32_e32 v0, 63, v1
	v_lshlrev_b32_e32 v2, 2, v0
	s_waitcnt lgkmcnt(0)
	global_load_dword v3, v2, s[4:5]
	global_load_dword v4, v2, s[4:5] offset:256
	global_load_dword v5, v2, s[4:5] offset:512
	s_nop 0
	global_load_dword v2, v2, s[4:5] offset:768
	v_readlane_b32 s2, v255, 10
	v_lshlrev_b32_e32 v6, 5, v1
	v_lshlrev_b32_e32 v7, 5, v0
	v_readlane_b32 s3, v255, 11
	v_readlane_b32 s9, v252, 61
	v_readlane_b32 s10, v252, 62
	v_readlane_b32 s11, v252, 63
	v_readlane_b32 s12, v253, 0
	v_readlane_b32 s13, v253, 1
	v_readlane_b32 s18, v253, 6
	v_readlane_b32 s19, v253, 7
	v_readlane_b32 s20, v253, 8
	v_readlane_b32 s21, v253, 9
	v_readlane_b32 s22, v253, 10
	v_readlane_b32 s23, v253, 11
	v_and_b32_e32 v6, 0x1e0, v6
	global_load_dwordx4 v[32:35], v7, s[2:3] offset:16
	global_load_dwordx4 v[36:39], v7, s[2:3]
	global_load_dwordx4 v[40:43], v6, s[0:1] offset:16
	global_load_dwordx4 v[44:47], v6, s[0:1]
	s_add_u32 s0, s8, s36
	s_addc_u32 s1, s9, s37
	v_readlane_b32 s8, v252, 40
	v_readlane_b32 s22, v252, 54
	v_readlane_b32 s23, v252, 55
	s_add_u32 s2, s22, s36
	v_readlane_b32 s20, v252, 52
	s_addc_u32 s3, s23, s37
	v_readlane_b32 s21, v252, 53
	global_load_dwordx4 v[48:51], v7, s[0:1] offset:16
	global_load_dwordx4 v[52:55], v7, s[0:1]
	s_add_u32 s0, s20, s36
	s_addc_u32 s1, s21, s37
	global_load_dwordx4 v[56:59], v7, s[2:3] offset:16
	global_load_dwordx4 v[60:63], v7, s[2:3]
	global_load_dwordx4 v[64:67], v7, s[0:1] offset:16
	global_load_dwordx4 v[68:71], v7, s[0:1]
	v_and_b32_e32 v7, 64, v185
	v_xor_b32_e32 v6, 32, v185
	v_add_u32_e32 v7, 64, v7
	v_cmp_lt_i32_e32 vcc, v6, v7
	v_xor_b32_e32 v8, 16, v185
	v_xor_b32_e32 v9, 8, v185
	v_cndmask_b32_e32 v6, v185, v6, vcc
	v_lshlrev_b32_e32 v6, 2, v6
	v_cmp_lt_i32_e32 vcc, v8, v7
	v_xor_b32_e32 v10, 4, v185
	v_xor_b32_e32 v11, 2, v185
	v_cndmask_b32_e32 v8, v185, v8, vcc
	v_lshlrev_b32_e32 v8, 2, v8
	v_cmp_lt_i32_e32 vcc, v9, v7
	v_xor_b32_e32 v12, 1, v185
	s_mov_b32 s8, s6
	s_cmpk_gt_i32 s8, 0xff
	v_readfirstlane_b32 s0, v1
	v_readlane_b32 s9, v252, 41
	v_readlane_b32 s10, v252, 42
	v_readlane_b32 s11, v252, 43
	v_readlane_b32 s12, v252, 44
	v_readlane_b32 s13, v252, 45
	v_readlane_b32 s14, v252, 46
	v_readlane_b32 s15, v252, 47
	v_readlane_b32 s16, v252, 48
	v_readlane_b32 s17, v252, 49
	v_readlane_b32 s18, v252, 50
	v_readlane_b32 s19, v252, 51
	s_waitcnt vmcnt(0)
	v_mul_f32_e32 v13, v3, v4
	ds_bpermute_b32 v13, v6, v13
	v_mul_f32_e32 v14, v5, v2
	ds_bpermute_b32 v6, v6, v14
	s_waitcnt lgkmcnt(0)
	v_fmac_f32_e32 v13, v3, v4
	v_cndmask_b32_e32 v4, v185, v9, vcc
	v_fmac_f32_e32 v6, v5, v2
	ds_bpermute_b32 v2, v8, v13
	ds_bpermute_b32 v3, v8, v6
	v_lshlrev_b32_e32 v147, 2, v4
	v_cmp_lt_i32_e32 vcc, v10, v7
	s_waitcnt lgkmcnt(1)
	v_add_f32_e32 v2, v13, v2
	s_waitcnt lgkmcnt(0)
	v_add_f32_e32 v3, v6, v3
	ds_bpermute_b32 v4, v147, v2
	ds_bpermute_b32 v5, v147, v3
	v_cndmask_b32_e32 v6, v185, v10, vcc
	v_lshlrev_b32_e32 v161, 2, v6
	v_cmp_lt_i32_e32 vcc, v11, v7
	s_waitcnt lgkmcnt(1)
	v_add_f32_e32 v2, v2, v4
	s_waitcnt lgkmcnt(0)
	v_add_f32_e32 v3, v3, v5
	ds_bpermute_b32 v4, v161, v2
	ds_bpermute_b32 v5, v161, v3
	v_cndmask_b32_e32 v6, v185, v11, vcc
	v_lshlrev_b32_e32 v178, 2, v6
	v_cmp_lt_i32_e32 vcc, v12, v7
	s_waitcnt lgkmcnt(1)
	v_add_f32_e32 v2, v2, v4
	s_waitcnt lgkmcnt(0)
	v_add_f32_e32 v3, v3, v5
	ds_bpermute_b32 v4, v178, v2
	ds_bpermute_b32 v5, v178, v3
	v_cndmask_b32_e32 v6, v185, v12, vcc
	v_lshlrev_b32_e32 v179, 2, v6
	s_waitcnt lgkmcnt(1)
	v_add_f32_e32 v4, v2, v4
	s_waitcnt lgkmcnt(0)
	v_add_f32_e32 v2, v3, v5
	ds_bpermute_b32 v5, v179, v4
	ds_bpermute_b32 v3, v179, v2
	s_cbranch_scc1 .LBB0_112
	v_readlane_b32 s2, v255, 3
	s_mov_b32 s1, 0x3fb8aa3b
	v_readlane_b32 s3, v255, 4
	v_cvt_f32_i32_e32 v6, s2
	s_mov_b32 s2, 0xc2ce8ed0
	s_waitcnt lgkmcnt(1)
	v_add_f32_e32 v4, v4, v5
	s_mov_b32 s3, 0x42b17218
	v_mul_f32_e32 v6, 0xbe99999a, v6
	v_mul_f32_e32 v7, 0x3fb8aa3b, v6
	v_fma_f32 v8, v6, s1, -v7
	v_rndne_f32_e32 v9, v7
	v_fmac_f32_e32 v8, 0x32a5705f, v6
	v_sub_f32_e32 v7, v7, v9
	v_add_f32_e32 v7, v7, v8
	v_cvt_i32_f32_e32 v9, v9
	v_exp_f32_e32 v7, v7
	v_cmp_ngt_f32_e32 vcc, s2, v6
	s_waitcnt lgkmcnt(0)
	v_add_f32_e32 v2, v2, v3
	v_and_b32_e32 v146, 31, v1
	v_ldexp_f32 v5, v7, v9
	v_cndmask_b32_e32 v5, 0, v5, vcc
	v_cmp_nlt_f32_e32 vcc, s3, v6
	v_mul_f32_e32 v6, 0x3fb8aa3b, v4
	v_fma_f32 v7, v4, s1, -v6
	v_rndne_f32_e32 v8, v6
	v_fmac_f32_e32 v7, 0x32a5705f, v4
	v_sub_f32_e32 v6, v6, v8
	v_add_f32_e32 v6, v6, v7
	v_exp_f32_e32 v6, v6
	v_cvt_i32_f32_e32 v7, v8
	v_cndmask_b32_e32 v5, v186, v5, vcc
	v_mov_b32_e32 v8, 0x3f4ccccd
	v_fmamk_f32 v5, v5, 0xbf19999a, v8
	v_ldexp_f32 v3, v6, v7
	v_mul_f32_e32 v6, 0x3fb8aa3b, v2
	v_fma_f32 v7, v2, s1, -v6
	v_rndne_f32_e32 v8, v6
	v_fmac_f32_e32 v7, 0x32a5705f, v2
	v_sub_f32_e32 v6, v6, v8
	v_add_f32_e32 v6, v6, v7
	v_exp_f32_e32 v6, v6
	v_cvt_i32_f32_e32 v7, v8
	v_cmp_ngt_f32_e32 vcc, s2, v4
	s_ashr_i32 s1, s0, 6
	v_readlane_b32 s6, v252, 22
	v_cndmask_b32_e32 v3, 0, v3, vcc
	v_cmp_nlt_f32_e32 vcc, s3, v4
	v_ldexp_f32 v4, v6, v7
	v_sub_f32_e32 v180, 1.0, v5
	v_cndmask_b32_e32 v3, v186, v3, vcc
	v_cmp_ngt_f32_e32 vcc, s2, v2
	s_and_b32 s2, s0, 0xffffffc0
	s_lshl_b32 s0, s0, 2
	v_cndmask_b32_e32 v4, 0, v4, vcc
	v_cmp_nlt_f32_e32 vcc, s3, v2
	s_and_b32 s0, s0, 0xffffff00
	s_ashr_i32 s3, s2, 31
	v_cndmask_b32_e32 v2, v186, v4, vcc
	v_sub_f32_e32 v2, v3, v2
	v_add_f32_e32 v148, v5, v2
	v_lshrrev_b32_e32 v3, 5, v0
	v_lshrrev_b32_e32 v2, 1, v1
	v_and_b32_e32 v112, 16, v2
	v_readlane_b32 s7, v252, 23
	v_lshlrev_b32_e32 v2, 6, v146
	v_lshl_add_u32 v5, v3, 13, s0
	v_bfe_u32 v1, v1, 5, 1
	s_lshl_b32 s0, s1, 14
	s_lshl_b64 s[4:5], s[2:3], 2
	v_lshl_add_u64 v[150:151], s[6:7], 0, v[112:113]
	v_or_b32_e32 v4, 0x800, v2
	v_lshl_or_b32 v5, v146, 2, v5
	v_lshlrev_b32_e32 v112, 12, v1
	v_or_b32_e32 v152, s2, v146
	v_mov_b32_e32 v153, s3
	s_add_i32 s0, s0, 0
	s_lshl_b32 s9, s1, 8
	s_lshl_b32 s10, s1, 3
	v_mov_b32_e32 v149, v148
	v_add_u32_e32 v181, 0, v5
	v_lshl_add_u64 v[158:159], v[152:153], 1, v[112:113]
	v_lshlrev_b32_e32 v160, 2, v1
	v_lshl_or_b32 v162, v3, 4, s4
	v_mov_b32_e32 v163, s5
	v_lshl_add_u32 v197, v0, 5, s0
	v_lshlrev_b32_e32 v164, 4, v0
	v_mov_b32_e32 v165, v113
	v_lshlrev_b32_e32 v112, 1, v2
	v_lshlrev_b32_e32 v166, 1, v4
	s_mov_b32 s11, s8

; __device__ __forceinline__ int tid_opaque() { int t = (int)threadIdx.x; asm volatile("" : "+v"(t)); return t; }
; __device__ __forceinline__ int bid_opaque() { int t = (int)blockIdx.x; asm volatile("" : "+s"(t)); return t; }
; #define CH_PREF(FP, L0, L1, cc) do { ldf_g(PTb + (size_t)(cc) * 4096, n0, lane, FP); const bf16_t* LC_ = LCb + (size_t)(cc) * 4096 + (q * 64 + lane) * 16; L0 = *(const u32x4*)LC_; L1 = *(const u32x4*)(LC_ + 8); } while (0)
; __device__ void chain_pass(unsigned char* lds, unsigned char* ws, int inst) {
;     const int tid = tid_opaque(), w = __builtin_amdgcn_readfirstlane(tid >> 6), lane = tid & 63, hi = lane >> 5, l32 = lane & 31;
;     const int q = w & 3, m0 = (q >> 1) * 32, n0 = (q & 1) * 32;
;     unsigned char* Shi = lds; unsigned char* Slo = lds + SLOT;
;     f32x16 S = zero16();
;     bf16x8 fpA[4], fpB[4]; u32x4 lcA0 = (u32x4){0u, 0u, 0u, 0u}, lcA1 = lcA0, lcB0 = lcA0, lcB1 = lcA0;
;     const bf16_t* PTb = (const bf16_t*)(ws + WS_PT) + (size_t)inst * 128 * 4096; bf16_t* LCb = (bf16_t*)(ws + WS_LC) + (size_t)inst * 128 * 4096;
;     ...
;     if (w < 4) CH_PREF(fpA, lcA0, lcA1, 0);
;     __syncthreads();
; __device__ void mixer_phase(const Params& P, int l, unsigned char* smem) {
;     unsigned char* ws = P.ws;
;     const int bid = bid_opaque(); const int tid0 = tid_opaque();
;     if (bid < 32) ck::chain_pass(smem, ws, bid);
.LBB0_113:
	s_andn2_b64 vcc, exec, s[0:1]
	s_cbranch_vccnz .LBB0_422
	v_readlane_b32 s0, v255, 7
	s_cmp_gt_i32 s0, 7
	s_mov_b64 s[0:1], -1
	s_cbranch_scc0 .LBB0_337
	v_readlane_b32 s0, v254, 50
	s_mov_b32 s4, s0
	v_readlane_b32 s28, v252, 24
	v_readlane_b32 s46, v252, 26
	s_mov_b32 s38, -2.0
	s_mov_b32 s40, 0xc1800000
	s_mov_b32 s42, 0xc1900000
	s_mov_b32 s44, 0xc1c00000
	s_mov_b32 s48, 0xc1d00000
	v_readlane_b32 s50, v254, 53
	v_mov_b32_e32 v150, v154
	s_cmp_gt_i32 s4, 31
	v_readlane_b32 s29, v252, 25
	v_readlane_b32 s47, v252, 27
	s_mov_b32 s39, 0xc0400000
	s_mov_b32 s41, 0xc1880000
	s_mov_b32 s43, 0xc1980000
	s_mov_b32 s45, 0xc1c80000
	s_mov_b32 s49, 0xc1d80000
	v_readlane_b32 s51, v254, 54
	s_cbranch_scc1 .LBB0_137
	v_mov_b32_e32 v6, v154
	s_mov_b64 s[6:7], -1
	v_readfirstlane_b32 s2, v6
	s_ashr_i32 s3, s2, 6
	s_and_b32 s8, s3, 3
	v_and_b32_e32 v0, 63, v6
	s_cmp_lt_i32 s3, 4
	s_cselect_b64 s[0:1], -1, 0
	v_lshrrev_b32_e32 v1, 2, v6
	v_lshlrev_b32_e32 v0, 4, v0
	s_and_b64 vcc, exec, s[0:1]
	v_and_b32_e32 v4, 8, v1
	v_lshl_or_b32 v0, s8, 10, v0
	s_cbranch_vccnz .LBB0_118
	v_and_b32_e32 v112, 8, v1
	v_mov_b32_e32 v1, v113
	s_mov_b64 s[6:7], 0
	s_waitcnt lgkmcnt(0)
	v_mov_b64_e32 v[2:3], v[112:113]

; __device__ __forceinline__ int tid_opaque() { int t = (int)threadIdx.x; asm volatile("" : "+v"(t)); return t; }
; __device__ __forceinline__ int bid_opaque() { int t = (int)blockIdx.x; asm volatile("" : "+s"(t)); return t; }
; __device__ __forceinline__ float bf2f(unsigned short u) { return __uint_as_float(((unsigned)u) << 16); }
; template <int MODE> __device__ void chunk_pass(unsigned char* lds, unsigned char* ws, const float* k_a) {
;     const int tid = tid_opaque(), w = __builtin_amdgcn_readfirstlane(tid >> 6), lane0 = tid & 63;
;     const int q = w & 3, m0 = (q >> 1) * 32, n0 = (q & 1) * 32;
;     const int bid = bid_opaque();
;     ...
;     float* segsum = (float*)(lds + 11 * SLOT); float* gC = segsum + 512; float* Lf = gC + 64; unsigned char* SC = (unsigned char*)(Lf + 4096);
;     const bf16_t* R = (const bf16_t*)(ws + WS_R); const bf16_t* V = (const bf16_t*)(ws + WS_V); const bf16_t* KK = (const bf16_t*)(ws + WS_KK); const bf16_t* Kb = (const bf16_t*)(ws + WS_K);
;     for (int ci = bid; ci < 4096; ci += (int)gridDim.x) {
;         const int inst = ci >> 7, c = ci & 127, b = inst >> 4, h = (inst >> 1) & 7, dir = inst & 1;
;         int lane = lane0; asm volatile("" : "+v"(lane)); const int hi = lane >> 5, l32 = lane & 31;
;         const float* LW = (const float*)(ws + (dir ? WS_WBK : WS_WF)); const bf16_t* Ag = (const bf16_t*)(ws + (dir ? WS_AB : WS_AF));
;         const int colbase = h * 64; const size_t tb = (size_t)b * SEQ;
;         const float kav = k_a[colbase + lane];
;         float kk[8], lw[8], a[8], kx[8], rr[8], vv[8];
; #pragma unroll
;         for (int i = 0; i < 8; ++i) { const int step = 64 * c + 8 * w + i; const size_t off = (tb + (size_t)(dir ? (SEQ - 1 - step) : step)) * 512 + colbase + lane;
;             kk[i] = bf2f(KK[off]); lw[i] = LW[off]; a[i] = bf2f(Ag[off]); kx[i] = bf2f(Kb[off]); rr[i] = bf2f(R[off]); vv[i] = bf2f(V[off]); }
;         float pf[8]; pf[0] = lw[0];
; #pragma unroll
;         for (int i = 1; i < 8; ++i) pf[i] = pf[i - 1] + lw[i];
;         segsum[w * 64 + lane] = pf[7];
;         __syncthreads();
;         float offs = 0.f, tot = 0.f;
; #pragma unroll
;         for (int jj = 0; jj < 8; ++jj) { const float sv = segsum[jj * 64 + lane]; if (jj < w) offs += sv; tot += sv; }
.LBB0_337:
	s_and_b64 vcc, exec, s[0:1]
	s_cbranch_vccz .LBB0_422
	v_mov_b32_e32 v0, v154
	v_readlane_b32 s0, v254, 50
	s_cmpk_gt_i32 s0, 0xfff
	v_readfirstlane_b32 s1, v0
	s_cbranch_scc1 .LBB0_422
	s_ashr_i32 s74, s1, 6
	s_lshl_b32 s2, s74, 5
	s_and_b32 s77, s2, 32
	s_and_b32 s2, s1, 0x3fffffc0
	s_lshl_b32 s2, s2, 2
	s_lshl_b32 s56, s74, 4
	s_add_i32 s80, s2, 0
	s_and_b32 s57, s56, 32
	s_lshl_b32 s79, s74, 3
	s_add_i32 s80, s80, 0x18c00
	s_cmp_lt_u32 s1, 64
	s_cselect_b64 s[50:51], -1, 0
	s_lshl_b32 s1, s74, 10
	s_and_b32 s38, s1, 0xc00
	s_cmp_gt_i32 s74, 0
	s_cselect_b64 s[4:5], -1, 0
	s_cmp_gt_i32 s74, 1
	s_cselect_b64 s[6:7], -1, 0
	s_cmp_gt_i32 s74, 2
	s_cselect_b64 s[8:9], -1, 0
	s_cmp_gt_i32 s74, 3
	s_cselect_b64 s[10:11], -1, 0
	s_cmp_gt_i32 s74, 4
	s_cselect_b64 s[12:13], -1, 0
	s_cmp_gt_i32 s74, 5
	s_cselect_b64 s[14:15], -1, 0
	s_cmp_gt_i32 s74, 6
	s_cselect_b64 s[16:17], -1, 0
	s_cmp_gt_i32 s74, 7
	s_cselect_b64 s[18:19], -1, 0
	s_add_i32 s82, 0, 0x12000
	s_cmp_lt_i32 s74, 4
	s_cselect_b64 s[70:71], -1, 0
	s_and_b64 s[2:3], s[70:71], exec
	v_readlane_b32 s2, v254, 28
	v_readlane_b32 s20, v254, 29
	s_movk_i32 s1, 0x480
	s_cselect_b32 s83, s2, s20
	v_cmp_gt_i32_e64 s[44:45], s1, v0
	s_cselect_b32 s75, s2, s82
	v_readlane_b32 s1, v254, 30
	v_readlane_b32 s2, v254, 31
	v_and_b32_e32 v67, 63, v0
	s_mulk_i32 s74, 0x240
	s_cselect_b32 s2, s1, s2
	s_cselect_b32 s3, s1, s82
	v_add_u32_e32 v70, 0xffffff00, v0
	v_lshl_add_u32 v71, v0, 4, s20
	s_lshl_b32 s39, s77, 1
	s_branch .LBB0_341

; __device__ __forceinline__ int tid_opaque() { int t = (int)threadIdx.x; asm volatile("" : "+v"(t)); return t; }
; #define PG8_WAIT_V(n) asm volatile("s_waitcnt vmcnt(" #n ")" ::: "memory")
; #define PG8_BAR __builtin_amdgcn_s_barrier()
; template <class Epi, class Sched, bool ALIGN_EPI = false, bool SP2 = false>
; __device__ __forceinline__ void gemm_phase(PG8_LAS unsigned char* lds, const Gemm g, const Sched& S, const Epi& E) {
;     const int tid = tid_opaque(), wid = __builtin_amdgcn_readfirstlane(tid >> 6), lane = tid & 63, wr = wid >> 2, wc = wid & 3, fr = lane & 15, fq = lane >> 4;
;     const int K = g.K, nt = K / BK;
;     unsigned voffA[2], voffB[2];
; #pragma unroll
;     for (int i = 0; i < 2; ++i) { int R, C; stage_rc(tid * 16 + i * 8192, R, C); const int Rb = Epi::PERM ? ((R & ~31) + perm32(R & 31)) : R;
;         voffA[i] = (unsigned)(R * K + C) * 2u; voffB[i] = (unsigned)(Rb * K + C) * 2u; }
;     const size_t kstep = (size_t)(BK * 2);
;     const size_t hstep = (size_t)HALF * K * 2;
;     const size_t tstep = 2 * hstep;
;     const unsigned ldsw = (unsigned)wid * 1024u;
;     const int aoff = lds_byte(wr * 64 + fr, fq * 8), boff = lds_byte(wc * 32 + fr, fq * 8);
;     ...
;     Unit cur, nxt; int ui = 0;
;     if (!S.next(0, cur)) return;
;     f32x4 acc[2][2][4][2];
; #pragma unroll
;     for (int a = 0; a < 2; ++a)
; #pragma unroll
;         for (int b = 0; b < 2; ++b)
; #pragma unroll
;             for (int m = 0; m < 4; ++m)
; #pragma unroll
;                 for (int n = 0; n < 2; ++n) acc[a][b][m][n] = (f32x4){0.f, 0.f, 0.f, 0.f};
;     bf16x8 At[4][2], B0[2][2], B1[2][2];
;     const char* cA = (const char*)g.A + (size_t)cur.pm * tstep; const char* cB = (const char*)g.Bt + (size_t)cur.pn * tstep;
;     S.a_ready(cur);
;     if constexpr (SP2) {
;         PG8_STAGE(PG8_SB(0, 0), cB, voffB); PG8_STAGE(PG8_SB(0, 1), cB + hstep, voffB); PG8_STAGE(PG8_SA(0, 0), cA, voffA); PG8_STAGE(PG8_SA(0, 1), cA + hstep, voffA);
;         if (wr == 1) PG8_BAR;
;         PG8_WAIT_V(2); PG8_BAR;
;         PG8_STAGE(PG8_SB(1, 0), cB + kstep, voffB); PG8_STAGE(PG8_SA(1, 0), cA + kstep, voffA); PG8_STAGE(PG8_SB(1, 1), cB + hstep + kstep, voffB);
;         PG8_WAIT_V(6); PG8_BAR;
;     } else {
;         PG8_STAGE(PG8_SB(0, 0), cB, voffB); PG8_STAGE(PG8_SA(0, 0), cA, voffA); PG8_STAGE(PG8_SB(0, 1), cB + hstep, voffB); PG8_STAGE(PG8_SA(0, 1), cA + hstep, voffA);
.LBB0_423:
	s_and_b64 vcc, exec, s[0:1]
	s_cbranch_vccz .LBB0_764
	s_cmp_gt_i32 s75, 2
	s_mov_b64 s[0:1], -1
	s_cbranch_scc0 .LBB0_737
	s_cmp_lt_i32 s75, 5
	s_cbranch_scc1 .LBB0_623
	s_cmp_gt_i32 s75, 5
	s_cbranch_scc0 .LBB0_547
	s_movk_i32 s0, 0x180
	s_movk_i32 s1, 0x400
	s_ashr_i32 s2, s1, 31
	s_lshr_b32 s2, s2, 24
	s_add_i32 s1, s1, s2
	s_ashr_i32 s2, s1, 8
	s_mov_b32 s28, s24
	s_lshl_b32 s8, s2, 6
	v_mov_b32_e32 v18, v154
	v_writelane_b32 v255, s54, 8
	s_cmp_ge_i32 s28, s8
	v_readfirstlane_b32 s4, v18
	v_writelane_b32 v255, s55, 9
	s_cbranch_scc1 .LBB0_449
	v_lshlrev_b32_e32 v0, 4, v18
	v_add_u32_e32 v1, 0x2000, v0
	v_ashrrev_i32_e32 v2, 31, v1
	v_lshrrev_b32_e32 v2, 22, v2
	v_add_u32_e32 v2, v1, v2
	v_ashrrev_i32_e32 v2, 10, v2
	s_waitcnt lgkmcnt(0)
	v_mul_i32_i24_e32 v3, 0x400, v2
	v_sub_u32_e32 v1, v1, v3
	v_lshrrev_b32_e32 v3, 4, v1
	v_bitop3_b32 v1, v3, v1, 32 bitop3:0x6c
	v_ashrrev_i32_e32 v3, 31, v1
	v_lshrrev_b32_e32 v3, 26, v3
	v_add_u32_e32 v3, v1, v3
	v_lshlrev_b32_e32 v5, 3, v2
	v_ashrrev_i32_e32 v4, 6, v3
	v_and_b32_e32 v5, -16, v5
	v_lshlrev_b32_e32 v2, 5, v2
	v_add_u32_e32 v5, v4, v5
	v_and_b32_e32 v12, 32, v2
	v_and_b32_e32 v2, 0xc0, v3
	v_and_b32_e32 v4, 3, v4
	s_mov_b32 s3, 0x7fffffe0
	v_lshrrev_b32_e32 v6, 2, v5
	v_lshlrev_b32_e32 v7, 1, v5
	v_sub_u32_e32 v1, v1, v2
	v_and_or_b32 v4, v5, s3, v4
	v_and_b32_e32 v6, 4, v6
	v_and_b32_e32 v7, 24, v7
	v_ashrrev_i16_sdwa v1, v183, sext(v1) dst_sel:DWORD dst_unused:UNUSED_PAD src0_sel:DWORD src1_sel:BYTE_0
	v_or3_b32 v4, v4, v6, v7
	v_bfe_i32 v13, v1, 0, 16
	v_mul_lo_u32 v4, v4, s0
	v_add_u32_e32 v1, v12, v13
	v_mul_lo_u32 v14, v5, s0
	v_add_lshl_u32 v138, v4, v1, 1
	v_add_lshl_u32 v140, v1, v14, 1
	v_bfe_i32 v1, v18, 27, 1
	v_lshrrev_b32_e32 v1, 22, v1
	v_add_u32_e32 v1, v0, v1
	v_and_b32_e32 v1, 0xfffffc00, v1
	v_sub_u32_e32 v0, v0, v1
	v_ashrrev_i32_e32 v2, 31, v18
	v_lshrrev_b32_e32 v1, 4, v0
	v_lshrrev_b32_e32 v2, 26, v2
	v_bitop3_b32 v1, v1, v0, 32 bitop3:0x6c
	v_ashrrev_i32_e32 v0, 31, v0
	v_add_u32_e32 v2, v18, v2
	v_lshrrev_b32_e32 v0, 26, v0
	v_ashrrev_i32_e32 v2, 6, v2
	v_add_u32_e32 v0, v1, v0
	v_lshlrev_b32_e32 v3, 3, v2
	v_readlane_b32 s6, v252, 6
	v_ashrrev_i32_e32 v0, 6, v0
	v_and_b32_e32 v3, -16, v3
	v_readlane_b32 s7, v252, 7
	v_add_u32_e32 v3, v0, v3
	v_and_b32_e32 v4, 3, v0
	s_ashr_i32 s76, s28, 31
	v_readlane_b32 s6, v252, 4
	v_and_or_b32 v4, v3, s3, v4
	s_lshr_b32 s3, s76, 29
	v_readlane_b32 s7, v252, 5
	v_mul_i32_i24_e32 v0, 64, v0
	s_add_i32 s3, s28, s3
	s_ashr_i32 s5, s4, 6
	s_ashr_i32 s1, s0, 31
	v_lshrrev_b32_e32 v5, 2, v3
	v_lshlrev_b32_e32 v6, 1, v3
	v_sub_u32_e32 v0, v1, v0
	s_lshl_b32 s59, s2, 3
	s_ashr_i32 s7, s3, 3
	s_and_b32 s3, s3, -8
	s_ashr_i32 s6, s4, 8
	s_lshl_b64 s[10:11], s[0:1], 8
	s_lshl_b64 s[12:13], s[0:1], 9
	s_lshl_b32 s29, s5, 10
	v_and_b32_e32 v5, 4, v5
	v_and_b32_e32 v6, 24, v6
	v_lshlrev_b32_e32 v2, 5, v2
	v_ashrrev_i16_sdwa v0, v183, sext(v0) dst_sel:DWORD dst_unused:UNUSED_PAD src0_sel:DWORD src1_sel:BYTE_0
	s_sub_i32 s3, s28, s3
	s_or_b32 s9, s59, 1
	v_or3_b32 v4, v4, v5, v6
	v_and_b32_e32 v15, 32, v2
	v_bfe_i32 v16, v0, 0, 16
	s_cmp_lt_i32 s3, 0
	v_mul_lo_u32 v4, v4, s0
	v_add_u32_e32 v0, v15, v16
	v_mul_lo_u32 v17, v3, s0
	s_mov_b32 s20, s9
	s_cselect_b32 s9, s9, s59
	s_abs_i32 s54, s59
	v_add_lshl_u32 v142, v4, v0, 1
	v_add_lshl_u32 v144, v0, v17, 1
	v_cvt_f32_u32_e32 v0, s54
	s_mul_i32 s3, s9, s3
	s_sub_i32 s9, 0, s54
	s_add_i32 s3, s3, s7
	v_rcp_iflag_f32_e32 v0, v0
	s_ashr_i32 s7, s3, 31
	s_bfe_i32 s2, s2, 0x1001c
	s_mov_b32 s21, s2
	v_mul_f32_e32 v0, 0x4f7ffffe, v0
	v_cvt_u32_f32_e32 v0, v0
	s_xor_b32 s2, s7, s2
	s_abs_i32 s7, s3
	v_mov_b32_e32 v143, v113
	v_readfirstlane_b32 s55, v0
	s_mul_i32 s9, s9, s55
	s_mul_hi_u32 s9, s55, s9
	s_add_i32 s55, s55, s9
	s_mul_hi_u32 s9, s7, s55
	s_mul_i32 s14, s9, s54
	s_sub_i32 s7, s7, s14
	s_add_i32 s14, s9, 1
	s_sub_i32 s15, s7, s54
	s_cmp_ge_u32 s7, s54
	s_cselect_b32 s9, s14, s9
	s_cselect_b32 s7, s15, s7
	s_add_i32 s14, s9, 1
	s_cmp_ge_u32 s7, s54
	s_cselect_b32 s7, s14, s9
	s_xor_b32 s7, s7, s2
	s_sub_i32 s2, s7, s2
	s_lshl_b32 s7, s2, 3
	s_sub_i32 s9, 64, s7
	s_min_i32 s9, s9, 8
	s_abs_i32 s15, s9
	v_cvt_f32_u32_e32 v0, s15
	s_sub_i32 s16, 0, s15
	s_mul_i32 s2, s2, s59
	s_sub_i32 s3, s3, s2
	v_rcp_iflag_f32_e32 v0, v0
	s_abs_i32 s14, s3
	s_xor_b32 s2, s3, s9
	s_ashr_i32 s2, s2, 31
	v_mul_f32_e32 v0, 0x4f7ffffe, v0
	v_cvt_u32_f32_e32 v0, v0
	v_mov_b32_e32 v139, v113
	v_mov_b32_e32 v145, v113
	v_mov_b32_e32 v141, v113
	v_readfirstlane_b32 s17, v0
	s_mul_i32 s16, s16, s17
	s_mul_hi_u32 s16, s17, s16
	s_add_i32 s17, s17, s16
	s_mul_hi_u32 s16, s14, s17
	s_mul_i32 s17, s16, s15
	s_sub_i32 s14, s14, s17
	s_add_i32 s17, s16, 1
	s_sub_i32 s18, s14, s15
	s_cmp_ge_u32 s14, s15
	s_cselect_b32 s16, s17, s16
	s_cselect_b32 s14, s18, s14
	s_add_i32 s17, s16, 1
	s_cmp_ge_u32 s14, s15
	s_cselect_b32 s14, s17, s16
	s_xor_b32 s14, s14, s2
	s_sub_i32 s2, s14, s2
	s_mul_i32 s9, s2, s9
	s_sub_i32 s3, s3, s9
	s_add_i32 s3, s3, s7
	s_lshr_b64 s[14:15], s[0:1], 23
	s_ashr_i32 s7, s3, 31
	s_ashr_i32 s15, s2, 31
	s_mul_i32 s7, s12, s7
	s_mul_hi_u32 s9, s12, s3
	s_mul_i32 s15, s12, s15
	s_mul_hi_u32 s16, s12, s2
	s_add_i32 s7, s9, s7
	s_mul_i32 s9, s14, s3
	s_add_i32 s15, s16, s15
	s_mul_i32 s14, s14, s2
	s_add_i32 s7, s7, s9
	s_add_i32 s15, s15, s14
	s_mul_i32 s14, s12, s2
	v_readlane_b32 s16, v252, 30
	v_readlane_b32 s17, v252, 31
	s_add_u32 s22, s16, s14
	s_addc_u32 s23, s17, s15
	s_add_i32 s64, s29, 0
	s_add_i32 m0, s64, 0x10000
	s_mul_i32 s9, s12, s3
	global_load_lds_dwordx4 v142, s[22:23]
	s_add_i32 m0, s64, 0x12000
	s_add_u32 s14, s22, s10
	global_load_lds_dwordx4 v138, s[22:23]
	s_addc_u32 s15, s23, s11
	s_add_i32 m0, s64, 0x14000
	v_lshl_add_u64 v[4:5], s[14:15], 0, v[142:143]
	global_load_lds_dwordx4 v142, s[14:15]
	s_add_i32 m0, s64, 0x16000
	v_lshl_add_u64 v[6:7], s[14:15], 0, v[138:139]
	global_load_lds_dwordx4 v138, s[14:15]
	v_readlane_b32 s14, v252, 12
	s_add_u32 s24, s14, s9
	v_readlane_b32 s9, v252, 13
	s_addc_u32 s25, s9, s7
	s_add_i32 s65, s64, 0x2000
	s_mov_b32 m0, s64
	s_add_u32 s14, s24, s10
	global_load_lds_dwordx4 v144, s[24:25]
	s_mov_b32 m0, s65
	s_addc_u32 s15, s25, s11
	s_add_i32 s70, s64, 0x4000
	global_load_lds_dwordx4 v140, s[24:25]
	s_mov_b32 m0, s70
	s_add_i32 s71, s64, 0x6000
	global_load_lds_dwordx4 v144, s[14:15]
	s_mov_b32 m0, s71
	s_cmp_eq_u32 s6, 1
	global_load_lds_dwordx4 v140, s[14:15]
	v_lshl_add_u64 v[0:1], s[22:23], 0, v[142:143]
	v_lshl_add_u64 v[2:3], s[22:23], 0, v[138:139]
	v_lshl_add_u64 v[8:9], s[24:25], 0, v[144:145]
	v_lshl_add_u64 v[10:11], s[24:25], 0, v[140:141]
	s_cselect_b64 vcc, -1, 0
	s_cmp_lg_u32 s6, 1
	s_cbranch_scc1 .LBB0_430
	s_barrier

; __device__ __forceinline__ int tid_opaque() { int t = (int)threadIdx.x; asm volatile("" : "+v"(t)); return t; }
; #define PG8_WAIT_V(n) asm volatile("s_waitcnt vmcnt(" #n ")" ::: "memory")
; #define PG8_BAR __builtin_amdgcn_s_barrier()
; template <class Epi, class Sched, bool ALIGN_EPI = false, bool SP2 = false>
; __device__ __forceinline__ void gemm_phase(PG8_LAS unsigned char* lds, const Gemm g, const Sched& S, const Epi& E) {
;     const int tid = tid_opaque(), wid = __builtin_amdgcn_readfirstlane(tid >> 6), lane = tid & 63, wr = wid >> 2, wc = wid & 3, fr = lane & 15, fq = lane >> 4;
;     const int K = g.K, nt = K / BK;
;     unsigned voffA[2], voffB[2];
; #pragma unroll
;     for (int i = 0; i < 2; ++i) { int R, C; stage_rc(tid * 16 + i * 8192, R, C); const int Rb = Epi::PERM ? ((R & ~31) + perm32(R & 31)) : R;
;         voffA[i] = (unsigned)(R * K + C) * 2u; voffB[i] = (unsigned)(Rb * K + C) * 2u; }
;     const size_t kstep = (size_t)(BK * 2);
;     const size_t hstep = (size_t)HALF * K * 2;
;     const size_t tstep = 2 * hstep;
;     const unsigned ldsw = (unsigned)wid * 1024u;
;     const int aoff = lds_byte(wr * 64 + fr, fq * 8), boff = lds_byte(wc * 32 + fr, fq * 8);
;     ...
;     Unit cur, nxt; int ui = 0;
;     if (!S.next(0, cur)) return;
;     f32x4 acc[2][2][4][2];
; #pragma unroll
;     for (int a = 0; a < 2; ++a)
; #pragma unroll
;         for (int b = 0; b < 2; ++b)
; #pragma unroll
;             for (int m = 0; m < 4; ++m)
; #pragma unroll
;                 for (int n = 0; n < 2; ++n) acc[a][b][m][n] = (f32x4){0.f, 0.f, 0.f, 0.f};
;     bf16x8 At[4][2], B0[2][2], B1[2][2];
;     const char* cA = (const char*)g.A + (size_t)cur.pm * tstep; const char* cB = (const char*)g.Bt + (size_t)cur.pn * tstep;
;     S.a_ready(cur);
;     if constexpr (SP2) {
;         PG8_STAGE(PG8_SB(0, 0), cB, voffB); PG8_STAGE(PG8_SB(0, 1), cB + hstep, voffB); PG8_STAGE(PG8_SA(0, 0), cA, voffA); PG8_STAGE(PG8_SA(0, 1), cA + hstep, voffA);
;         if (wr == 1) PG8_BAR;
;         PG8_WAIT_V(2); PG8_BAR;
;         PG8_STAGE(PG8_SB(1, 0), cB + kstep, voffB); PG8_STAGE(PG8_SA(1, 0), cA + kstep, voffA); PG8_STAGE(PG8_SB(1, 1), cB + hstep + kstep, voffB);
;         PG8_WAIT_V(6); PG8_BAR;
;     } else {
;         PG8_STAGE(PG8_SB(0, 0), cB, voffB); PG8_STAGE(PG8_SA(0, 0), cA, voffA); PG8_STAGE(PG8_SB(0, 1), cB + hstep, voffB); PG8_STAGE(PG8_SA(0, 1), cA + hstep, voffA);
.LBB0_624:
	s_cmp_gt_i32 s75, 3
	s_mov_b64 s[0:1], -1
	s_cbranch_scc0 .LBB0_656
	s_movk_i32 s0, 0x400
	s_movk_i32 s1, 0x1600
	s_ashr_i32 s2, s1, 31
	s_lshr_b32 s2, s2, 24
	s_add_i32 s1, s1, s2
	s_ashr_i32 s2, s1, 8
	s_mov_b32 s50, s24
	s_lshl_b32 s8, s2, 6
	v_mov_b32_e32 v18, v154
	s_cmp_ge_i32 s50, s8
	v_readfirstlane_b32 s4, v18
	s_cbranch_scc1 .LBB0_655
	v_lshlrev_b32_e32 v0, 4, v18
	v_add_u32_e32 v1, 0x2000, v0
	v_ashrrev_i32_e32 v2, 31, v1
	v_lshrrev_b32_e32 v2, 22, v2
	v_add_u32_e32 v2, v1, v2
	v_ashrrev_i32_e32 v2, 10, v2
	s_waitcnt lgkmcnt(0)
	v_mul_i32_i24_e32 v3, 0x400, v2
	v_sub_u32_e32 v1, v1, v3
	v_lshrrev_b32_e32 v3, 4, v1
	v_bitop3_b32 v1, v3, v1, 32 bitop3:0x6c
	v_ashrrev_i32_e32 v3, 31, v1
	v_lshrrev_b32_e32 v3, 26, v3
	v_add_u32_e32 v3, v1, v3
	v_lshlrev_b32_e32 v5, 3, v2
	v_ashrrev_i32_e32 v4, 6, v3
	v_and_b32_e32 v5, -16, v5
	v_lshlrev_b32_e32 v2, 5, v2
	v_add_u32_e32 v5, v4, v5
	v_and_b32_e32 v12, 32, v2
	v_and_b32_e32 v2, 0xc0, v3
	v_and_b32_e32 v4, 3, v4
	s_mov_b32 s3, 0x7fffffe0
	v_lshrrev_b32_e32 v6, 2, v5
	v_lshlrev_b32_e32 v7, 1, v5
	v_sub_u32_e32 v1, v1, v2
	v_and_or_b32 v4, v5, s3, v4
	v_and_b32_e32 v6, 4, v6
	v_and_b32_e32 v7, 24, v7
	v_ashrrev_i16_sdwa v1, v183, sext(v1) dst_sel:DWORD dst_unused:UNUSED_PAD src0_sel:DWORD src1_sel:BYTE_0
	v_or3_b32 v4, v4, v6, v7
	v_bfe_i32 v13, v1, 0, 16
	v_mul_lo_u32 v4, v4, s0
	v_add_u32_e32 v1, v12, v13
	v_mul_lo_u32 v14, v5, s0
	v_add_lshl_u32 v130, v4, v1, 1
	v_add_lshl_u32 v132, v1, v14, 1
	v_bfe_i32 v1, v18, 27, 1
	v_lshrrev_b32_e32 v1, 22, v1
	v_add_u32_e32 v1, v0, v1
	v_and_b32_e32 v1, 0xfffffc00, v1
	v_sub_u32_e32 v0, v0, v1
	v_ashrrev_i32_e32 v2, 31, v18
	v_lshrrev_b32_e32 v1, 4, v0
	v_lshrrev_b32_e32 v2, 26, v2
	v_bitop3_b32 v1, v1, v0, 32 bitop3:0x6c
	v_ashrrev_i32_e32 v0, 31, v0
	v_add_u32_e32 v2, v18, v2
	v_lshrrev_b32_e32 v0, 26, v0
	v_ashrrev_i32_e32 v2, 6, v2
	v_add_u32_e32 v0, v1, v0
	v_lshlrev_b32_e32 v3, 3, v2
	v_ashrrev_i32_e32 v0, 6, v0
	v_and_b32_e32 v3, -16, v3
	v_add_u32_e32 v3, v0, v3
	v_and_b32_e32 v4, 3, v0
	v_mul_i32_i24_e32 v0, 64, v0
	v_lshrrev_b32_e32 v5, 2, v3
	v_lshlrev_b32_e32 v6, 1, v3
	v_sub_u32_e32 v0, v1, v0
	v_and_or_b32 v4, v3, s3, v4
	v_and_b32_e32 v5, 4, v5
	v_and_b32_e32 v6, 24, v6
	v_lshlrev_b32_e32 v2, 5, v2
	v_ashrrev_i16_sdwa v0, v183, sext(v0) dst_sel:DWORD dst_unused:UNUSED_PAD src0_sel:DWORD src1_sel:BYTE_0
	s_mov_b64 s[40:41], s[54:55]
	v_or3_b32 v4, v4, v5, v6
	v_and_b32_e32 v15, 32, v2
	v_bfe_i32 v16, v0, 0, 16
	s_lshl_b32 s54, s2, 3
	s_mov_b64 s[38:39], s[64:65]
	v_mul_lo_u32 v4, v4, s0
	v_add_u32_e32 v0, v15, v16
	v_mul_lo_u32 v17, v3, s0
	s_abs_i32 s65, s54
	v_add_lshl_u32 v134, v4, v0, 1
	v_add_lshl_u32 v136, v0, v17, 1
	v_cvt_f32_u32_e32 v0, s65
	s_ashr_i32 s55, s50, 31
	s_lshr_b32 s3, s55, 29
	s_add_i32 s3, s50, s3
	v_rcp_iflag_f32_e32 v0, v0
	s_ashr_i32 s7, s3, 3
	s_and_b32 s3, s3, -8
	s_sub_i32 s3, s50, s3
	v_mul_f32_e32 v0, 0x4f7ffffe, v0
	v_cvt_u32_f32_e32 v0, v0
	s_lshr_b32 s9, s3, 31
	s_or_b32 s9, s9, s54
	s_mul_i32 s3, s9, s3
	s_sub_i32 s9, 0, s65
	v_readfirstlane_b32 s14, v0
	s_add_i32 s3, s3, s7
	s_mul_i32 s9, s9, s14
	s_ashr_i32 s7, s3, 31
	s_bfe_i32 s42, s2, 0x1001c
	s_mul_hi_u32 s9, s14, s9
	s_xor_b32 s2, s7, s42
	s_abs_i32 s7, s3
	s_add_i32 s43, s14, s9
	s_mul_hi_u32 s9, s7, s43
	s_mul_i32 s14, s9, s65
	s_ashr_i32 s5, s4, 6
	s_ashr_i32 s1, s0, 31
	s_sub_i32 s7, s7, s14
	s_ashr_i32 s6, s4, 8
	s_lshl_b64 s[10:11], s[0:1], 8
	s_lshl_b64 s[12:13], s[0:1], 9
	s_lshl_b32 s51, s5, 10
	s_add_i32 s14, s9, 1
	s_sub_i32 s15, s7, s65
	s_cmp_ge_u32 s7, s65
	s_cselect_b32 s9, s14, s9
	s_cselect_b32 s7, s15, s7
	s_add_i32 s14, s9, 1
	s_cmp_ge_u32 s7, s65
	s_cselect_b32 s7, s14, s9
	s_xor_b32 s7, s7, s2
	s_sub_i32 s2, s7, s2
	s_lshl_b32 s7, s2, 3
	s_sub_i32 s9, 64, s7
	s_min_i32 s9, s9, 8
	s_abs_i32 s15, s9
	v_cvt_f32_u32_e32 v0, s15
	s_sub_i32 s16, 0, s15
	s_mul_i32 s2, s2, s54
	s_sub_i32 s2, s3, s2
	v_rcp_iflag_f32_e32 v0, v0
	s_abs_i32 s14, s2
	s_xor_b32 s3, s2, s9
	s_ashr_i32 s3, s3, 31
	v_mul_f32_e32 v0, 0x4f7ffffe, v0
	v_cvt_u32_f32_e32 v0, v0
	v_mov_b32_e32 v135, v113
	v_mov_b32_e32 v131, v113
	v_mov_b32_e32 v137, v113
	v_readfirstlane_b32 s17, v0
	s_mul_i32 s16, s16, s17
	s_mul_hi_u32 s16, s17, s16
	s_add_i32 s17, s17, s16
	s_mul_hi_u32 s16, s14, s17
	s_mul_i32 s17, s16, s15
	s_sub_i32 s14, s14, s17
	s_add_i32 s17, s16, 1
	s_sub_i32 s18, s14, s15
	s_cmp_ge_u32 s14, s15
	s_cselect_b32 s16, s17, s16
	s_cselect_b32 s14, s18, s14
	s_add_i32 s17, s16, 1
	s_cmp_ge_u32 s14, s15
	s_cselect_b32 s14, s17, s16
	s_xor_b32 s14, s14, s3
	s_sub_i32 s3, s14, s3
	s_mul_i32 s9, s3, s9
	s_sub_i32 s2, s2, s9
	s_add_i32 s2, s2, s7
	s_lshr_b64 s[14:15], s[0:1], 23
	s_ashr_i32 s7, s2, 31
	s_ashr_i32 s15, s3, 31
	s_mul_i32 s7, s12, s7
	s_mul_hi_u32 s9, s12, s2
	s_mul_i32 s15, s12, s15
	s_mul_hi_u32 s16, s12, s3
	s_add_i32 s7, s9, s7
	s_mul_i32 s9, s14, s2
	s_add_i32 s15, s16, s15
	s_mul_i32 s14, s14, s3
	s_add_i32 s7, s7, s9
	s_add_i32 s15, s15, s14
	s_mul_i32 s14, s12, s3
	s_add_u32 s22, s26, s14
	s_addc_u32 s23, s27, s15
	s_add_i32 s71, s51, 0
	s_add_i32 m0, s71, 0x10000
	s_mul_i32 s9, s12, s2
	global_load_lds_dwordx4 v134, s[22:23]
	s_add_i32 m0, s71, 0x12000
	s_add_u32 s14, s22, s10
	global_load_lds_dwordx4 v130, s[22:23]
	s_addc_u32 s15, s23, s11
	s_add_i32 m0, s71, 0x14000
	v_lshl_add_u64 v[4:5], s[14:15], 0, v[134:135]
	global_load_lds_dwordx4 v134, s[14:15]
	s_add_i32 m0, s71, 0x16000
	s_add_u32 s24, s96, s9
	s_addc_u32 s25, s97, s7
	s_add_i32 s77, s71, 0x2000
	global_load_lds_dwordx4 v130, s[14:15]
	s_mov_b32 m0, s71
	s_add_u32 s16, s24, s10
	global_load_lds_dwordx4 v136, s[24:25]
	s_mov_b32 m0, s77
	s_addc_u32 s17, s25, s11
	s_add_i32 s64, s71, 0x4000
	v_lshl_add_u64 v[6:7], s[14:15], 0, v[130:131]
	global_load_lds_dwordx4 v132, s[24:25]
	s_mov_b32 m0, s64
	s_add_i32 s14, s71, 0x6000
	global_load_lds_dwordx4 v136, s[16:17]
	s_mov_b32 m0, s14
	v_mov_b32_e32 v133, v113
	global_load_lds_dwordx4 v132, s[16:17]
	s_cmp_eq_u32 s6, 1
	s_mov_b64 s[36:37], s[56:57]
	v_lshl_add_u64 v[0:1], s[22:23], 0, v[134:135]
	v_lshl_add_u64 v[2:3], s[22:23], 0, v[130:131]
	v_lshl_add_u64 v[8:9], s[24:25], 0, v[136:137]
	v_lshl_add_u64 v[10:11], s[24:25], 0, v[132:133]
	s_cselect_b64 s[44:45], -1, 0
	s_cmp_lg_u32 s6, 1
	s_cbranch_scc1 .LBB0_628
	s_barrier

; __device__ __forceinline__ int tid_opaque() { int t = (int)threadIdx.x; asm volatile("" : "+v"(t)); return t; }
; __device__ __forceinline__ int bid_opaque() { int t = (int)blockIdx.x; asm volatile("" : "+s"(t)); return t; }
; __device__ __forceinline__ unsigned short f2bf(float f) { return (unsigned short)(pk2(f, 0.f) & 0xffffu); }
; __device__ __forceinline__ void cvt_tile(unsigned char* lds, const float* src, int ld, int n_begin, int K, bf16_t* dst, int Kd, int koff, int mode, int roff, int t, int tid) {
;     const int ntk = Kd / 64; unsigned short* tile = (unsigned short*)lds;
;     const int tn = t / ntk, tk = t - tn * ntk; const int n0 = tn * 64, k0 = tk * 64;
;     const bool valid = (src != nullptr) && (k0 >= koff) && (k0 < koff + K);
;     __syncthreads();
;     if (valid) {
; #pragma unroll
;         for (int it = 0; it < 2; ++it) { const int idx = tid + 512 * it, kr = idx >> 4, nc4 = idx & 15;
;             const f32x4 v = *(const f32x4*)(src + (size_t)(k0 - koff + kr) * ld + n_begin + n0 + 4 * nc4);
; #pragma unroll
;             for (int j = 0; j < 4; ++j) tile[(4 * nc4 + j) * 66 + kr] = f2bf(v[j]); }
;     }
;     __syncthreads();
;     { const int n = tid >> 3, kc = (tid & 7) * 8; u32x4 w = (u32x4){0u, 0u, 0u, 0u};
;       if (valid) { const unsigned* tp = (const unsigned*)(tile + n * 66 + kc); w.x = tp[0]; w.y = tp[1]; w.z = tp[2]; w.w = tp[3]; }
;       const int nl = n0 + n; const int drow = (mode == 0) ? (nl + roff) : (256 * (nl >> 7) + (nl & 127) + roff);
;       *(u32x4*)(dst + (size_t)drow * Kd + k0 + kc) = w; }
; }
; __device__ __forceinline__ void cvt_job(unsigned char* lds, const float* src, int ld, int n_begin, int n_count, int K, bf16_t* dst, int Kd, int koff, int mode, int roff, int& cum) {
;     const int tid = tid_opaque(), G = gridDim.x; const int bid = bid_opaque();
;     const int ntiles = (n_count / 64) * (Kd / 64);
;     const int start = (int)(((unsigned)bid + (unsigned)G - (unsigned)(cum % G)) % (unsigned)G);
;     for (int t = start; t < ntiles; t += G) cvt_tile(lds, src, ld, n_begin, K, dst, Kd, koff, mode, roff, t, tid);
.LBB0_656:
	s_andn2_b64 vcc, exec, s[0:1]
	s_cbranch_vccnz .LBB0_736
	v_readlane_b32 s0, v255, 3
	v_readlane_b32 s1, v255, 4
	s_mov_b32 s2, s0
	s_ashr_i32 s3, s0, 31
	v_readlane_b32 s4, v253, 16
	s_mul_hi_i32 s1, s0, 0x1580000
	s_mov_b64 s[20:21], s[2:3]
	s_mul_i32 s0, s0, 0x1580000
	v_readlane_b32 s14, v253, 26
	v_mov_b32_e32 v0, v154
	s_mov_b32 s2, s24
	v_readlane_b32 s15, v253, 27
	s_add_u32 s0, s14, s0
	s_addc_u32 s1, s15, s1
	s_add_i32 s2, s2, s94
	v_readlane_b32 s3, v254, 10
	s_mul_hi_u32 s3, s2, s3
	s_mul_i32 s3, s3, s94
	s_sub_i32 s2, s2, s3
	s_sub_i32 s3, s2, s94
	s_cmp_ge_u32 s2, s94
	s_cselect_b32 s2, s3, s2
	s_sub_i32 s3, s2, s94
	v_readlane_b32 s12, v253, 24
	v_readlane_b32 s13, v253, 25
	v_readlane_b32 s18, v253, 30
	v_readlane_b32 s19, v253, 31
	s_cmp_ge_u32 s2, s94
	s_cselect_b32 s2, s3, s2
	v_readlane_b32 s14, v252, 30
	v_readlane_b32 s12, v252, 34
	v_readlane_b32 s18, v252, 38
	s_cmpk_gt_i32 s2, 0x1df
	v_readlane_b32 s15, v252, 31
	v_readlane_b32 s13, v252, 35
	v_readlane_b32 s19, v252, 39
	v_readlane_b32 s5, v253, 17
	v_readlane_b32 s6, v253, 18
	v_readlane_b32 s7, v253, 19
	v_readlane_b32 s8, v253, 20
	v_readlane_b32 s9, v253, 21
	v_readlane_b32 s10, v253, 22
	v_readlane_b32 s11, v253, 23
	v_readlane_b32 s16, v253, 28
	v_readlane_b32 s17, v253, 29
	s_cbranch_scc1 .LBB0_664
	v_lshlrev_b32_e32 v1, 2, v0
	v_ashrrev_i32_e32 v6, 4, v0
	s_waitcnt lgkmcnt(0)
	v_add_u32_e32 v3, 0x200, v0
	v_ashrrev_i32_e32 v8, 3, v0
	v_lshlrev_b32_e32 v0, 3, v0
	v_and_b32_e32 v1, 60, v1
	v_ashrrev_i32_e32 v7, 4, v3
	v_and_b32_e32 v0, 56, v0
	s_movk_i32 s3, 0x84
	v_lshlrev_b32_e32 v112, 2, v1
	v_lshl_add_u32 v2, v6, 1, 0
	v_mul_u32_u24_e32 v1, 0x84, v1
	v_lshl_add_u32 v3, v7, 1, 0
	v_mul_lo_u32 v9, v8, s3
	v_lshlrev_b32_e32 v10, 1, v0
	v_lshl_add_u64 v[4:5], s[0:1], 0, v[112:113]
	v_add3_u32 v9, 0, v9, v10
	s_lshl_b32 s3, s2, 6
	v_add_u32_e32 v10, v2, v1
	v_add_u32_e32 v11, v3, v1
	v_lshlrev_b32_e32 v112, 1, v0
	s_branch .LBB0_660

; template <class Epi, class Sched, bool ALIGN_EPI = false, bool SP2 = false>
; __device__ __forceinline__ void gemm_phase(PG8_LAS unsigned char* lds, const Gemm g, const Sched& S, const Epi& E) {
;     const int tid = tid_opaque(), wid = __builtin_amdgcn_readfirstlane(tid >> 6), lane = tid & 63, wr = wid >> 2, wc = wid & 3, fr = lane & 15, fq = lane >> 4;
;     const int K = g.K, nt = K / BK;
;     unsigned voffA[2], voffB[2];
; #pragma unroll
;     for (int i = 0; i < 2; ++i) { int R, C; stage_rc(tid * 16 + i * 8192, R, C); const int Rb = Epi::PERM ? ((R & ~31) + perm32(R & 31)) : R;
;         voffA[i] = (unsigned)(R * K + C) * 2u; voffB[i] = (unsigned)(Rb * K + C) * 2u; }
;     const size_t kstep = (size_t)(BK * 2);
;     const size_t hstep = (size_t)HALF * K * 2;
;     const size_t tstep = 2 * hstep;
;     const unsigned ldsw = (unsigned)wid * 1024u;
;     const int aoff = lds_byte(wr * 64 + fr, fq * 8), boff = lds_byte(wc * 32 + fr, fq * 8);
;     ...
;     Unit cur, nxt; int ui = 0;
;     if (!S.next(0, cur)) return;
;     f32x4 acc[2][2][4][2];
; #pragma unroll
;     for (int a = 0; a < 2; ++a)
; #pragma unroll
;         for (int b = 0; b < 2; ++b)
; #pragma unroll
;             for (int m = 0; m < 4; ++m)
; #pragma unroll
;                 for (int n = 0; n < 2; ++n) acc[a][b][m][n] = (f32x4){0.f, 0.f, 0.f, 0.f};
;     bf16x8 At[4][2], B0[2][2], B1[2][2];
;     const char* cA = (const char*)g.A + (size_t)cur.pm * tstep; const char* cB = (const char*)g.Bt + (size_t)cur.pn * tstep;
;     S.a_ready(cur);
;     if constexpr (SP2) {
;         PG8_STAGE(PG8_SB(0, 0), cB, voffB); PG8_STAGE(PG8_SB(0, 1), cB + hstep, voffB); PG8_STAGE(PG8_SA(0, 0), cA, voffA); PG8_STAGE(PG8_SA(0, 1), cA + hstep, voffA);
;         if (wr == 1) PG8_BAR;
;         PG8_WAIT_V(2); PG8_BAR;
; __global__ void __launch_bounds__(512, 2) mega_fwd(Params P) {
;     ...
;         const float* xcur = (l == 0 && k <= 2) ? P.in[0] : P.out;
;     ...
;         for (int rep = 0; rep < (((REP_MASK >> k) & 1) ? 2 : 1); ++rep)
;         switch (ONLY_K >= 0 ? ONLY_K : k) {
;         case 0: cvt_ffn(smem, ws, P.in[2] + (size_t)l * DM * NFF, P.in[3] + (size_t)l * DFF * DM); norm_rows(xcur, P.in[1] + l * DM, XN); break;
;         case 1: case 13: { EpiSwiGLU E{H}; run_gemm(smem, XN, WA, NFF, DM, E); } break;
;         case 2: { EpiResid E{xcur, P.out, 0.5f}; run_gemm(smem, H, WB, DM, DFF, E); } break;
.LBB0_737:
	s_andn2_b64 vcc, exec, s[0:1]
	s_mov_b64 s[42:43], 0
	s_cbranch_vccnz .LBB0_764
	s_add_i32 s0, s92, 14
	s_cmp_lt_u32 s0, 29
	s_cselect_b64 s[0:1], -1, 0
	s_cmp_lt_i32 s75, 3
	s_cselect_b64 s[2:3], -1, 0
	s_and_b64 s[0:1], s[0:1], s[2:3]
	s_and_b64 s[0:1], s[0:1], exec
	v_readlane_b32 s0, v253, 16
	v_readlane_b32 s1, v253, 17
	s_cselect_b32 s1, s1, s89
	s_cselect_b32 s0, s0, s88
	v_writelane_b32 v255, s0, 12
	s_cmp_gt_i32 s75, 0
	s_mov_b64 s[42:43], -1
	v_writelane_b32 v255, s1, 13
	v_readlane_b32 s2, v253, 18
	v_readlane_b32 s3, v253, 19
	v_readlane_b32 s4, v253, 20
	v_readlane_b32 s5, v253, 21
	v_readlane_b32 s6, v253, 22
	v_readlane_b32 s7, v253, 23
	v_readlane_b32 s8, v253, 24
	v_readlane_b32 s9, v253, 25
	v_readlane_b32 s10, v253, 26
	v_readlane_b32 s11, v253, 27
	v_readlane_b32 s12, v253, 28
	v_readlane_b32 s13, v253, 29
	v_readlane_b32 s14, v253, 30
	v_readlane_b32 s15, v253, 31
	s_cbranch_scc0 .LBB0_764
	s_cmp_gt_i32 s75, 1
	s_mov_b64 s[54:55], -1
	s_cbranch_scc0 .LBB0_763
	s_movk_i32 s4, 0xb00
	s_movk_i32 s0, 0x400
	s_ashr_i32 s1, s0, 31
	s_lshr_b32 s1, s1, 24
	s_add_i32 s0, s0, s1
	s_ashr_i32 s12, s0, 8
	s_mov_b32 s2, s24
	s_lshl_b32 s0, s12, 6
	v_mov_b32_e32 v12, v154
	s_cmp_ge_i32 s2, s0
	v_readfirstlane_b32 s1, v12
	s_cbranch_scc1 .LBB0_762
	v_lshlrev_b32_e32 v2, 4, v12
	v_add_u32_e32 v0, 0x2000, v2
	v_ashrrev_i32_e32 v1, 31, v0
	v_lshrrev_b32_e32 v1, 22, v1
	v_add_u32_e32 v1, v0, v1
	v_ashrrev_i32_e32 v1, 10, v1
	s_waitcnt lgkmcnt(0)
	v_mul_i32_i24_e32 v3, 0x400, v1
	v_sub_u32_e32 v0, v0, v3
	v_lshrrev_b32_e32 v3, 4, v0
	v_bitop3_b32 v3, v3, v0, 32 bitop3:0x6c
	v_ashrrev_i32_e32 v0, 31, v3
	v_lshrrev_b32_e32 v0, 26, v0
	v_add_u32_e32 v4, v3, v0
	v_lshlrev_b32_e32 v5, 3, v1
	v_ashrrev_i32_e32 v0, 6, v4
	v_and_b32_e32 v5, 0x7ffffff0, v5
	v_add_u32_e32 v5, v0, v5
	v_lshlrev_b32_e32 v0, 5, v1
	v_and_b32_e32 v0, 32, v0
	v_mad_u64_u32 v[0:1], s[14:15], v5, s4, v[0:1]
	v_and_b32_e32 v1, 0xc0, v4
	v_sub_u32_e32 v1, v3, v1
	v_ashrrev_i16_sdwa v1, v183, sext(v1) dst_sel:DWORD dst_unused:UNUSED_PAD src0_sel:DWORD src1_sel:BYTE_0
	v_bfe_i32 v1, v1, 0, 16
	v_add_lshl_u32 v130, v0, v1, 1
	v_bfe_i32 v0, v12, 27, 1
	v_lshrrev_b32_e32 v0, 22, v0
	v_add_u32_e32 v0, v2, v0
	v_and_b32_e32 v0, 0xfffffc00, v0
	v_sub_u32_e32 v0, v2, v0
	v_lshrrev_b32_e32 v1, 4, v0
	v_bitop3_b32 v2, v1, v0, 32 bitop3:0x6c
	v_ashrrev_i32_e32 v0, 31, v0
	v_lshrrev_b32_e32 v0, 26, v0
	v_add_u32_e32 v0, v2, v0
	v_ashrrev_i32_e32 v3, 6, v0
	v_ashrrev_i32_e32 v0, 31, v12
	v_lshrrev_b32_e32 v0, 26, v0
	v_add_u32_e32 v0, v12, v0
	v_ashrrev_i32_e32 v0, 6, v0
	v_lshlrev_b32_e32 v1, 3, v0
	v_and_b32_e32 v1, 0x7ffffff0, v1
	v_lshlrev_b32_e32 v0, 5, v0
	s_ashr_i32 s25, s2, 31
	v_add_u32_e32 v1, v3, v1
	v_and_b32_e32 v0, 32, v0
	s_lshr_b32 s13, s25, 29
	v_mad_u64_u32 v[0:1], s[14:15], v1, s4, v[0:1]
	s_add_i32 s13, s2, s13
	s_ashr_i32 s6, s1, 6
	s_ashr_i32 s5, s4, 31
	v_mul_i32_i24_e32 v1, 64, v3
	s_lshl_b32 s24, s12, 3
	s_ashr_i32 s14, s13, 3
	s_and_b32 s13, s13, -8
	s_ashr_i32 s7, s1, 8
	s_lshl_b64 s[8:9], s[4:5], 8
	s_lshl_b64 s[10:11], s[4:5], 9
	s_lshl_b32 s3, s6, 10
	v_sub_u32_e32 v1, v2, v1
	s_sub_i32 s13, s2, s13
	s_or_b32 s28, s24, 1
	v_ashrrev_i16_sdwa v1, v183, sext(v1) dst_sel:DWORD dst_unused:UNUSED_PAD src0_sel:DWORD src1_sel:BYTE_0
	s_cmp_lt_i32 s13, 0
	v_bfe_i32 v1, v1, 0, 16
	s_cselect_b32 s15, s28, s24
	s_abs_i32 s48, s24
	v_add_lshl_u32 v112, v0, v1, 1
	v_cvt_f32_u32_e32 v0, s48
	s_mul_i32 s13, s15, s13
	s_sub_i32 s15, 0, s48
	s_add_i32 s13, s13, s14
	v_rcp_iflag_f32_e32 v0, v0
	s_ashr_i32 s14, s13, 31
	s_bfe_i32 s29, s12, 0x1001c
	s_xor_b32 s12, s14, s29
	v_mul_f32_e32 v0, 0x4f7ffffe, v0
	v_cvt_u32_f32_e32 v0, v0
	s_abs_i32 s14, s13
	v_mov_b32_e32 v131, v113
	s_mov_b64 s[42:43], s[64:65]
	v_readfirstlane_b32 s49, v0
	s_mul_i32 s15, s15, s49
	s_mul_hi_u32 s15, s49, s15
	s_add_i32 s49, s49, s15
	s_mul_hi_u32 s15, s14, s49
	s_mul_i32 s16, s15, s48
	s_sub_i32 s14, s14, s16
	s_add_i32 s16, s15, 1
	s_sub_i32 s17, s14, s48
	s_cmp_ge_u32 s14, s48
	s_cselect_b32 s15, s16, s15
	s_cselect_b32 s14, s17, s14
	s_add_i32 s16, s15, 1
	s_cmp_ge_u32 s14, s48
	s_cselect_b32 s14, s16, s15
	s_xor_b32 s14, s14, s12
	s_sub_i32 s12, s14, s12
	s_lshl_b32 s14, s12, 3
	s_sub_i32 s15, 64, s14
	s_min_i32 s15, s15, 8
	s_abs_i32 s17, s15
	v_cvt_f32_u32_e32 v0, s17
	s_sub_i32 s18, 0, s17
	s_mul_i32 s12, s12, s24
	s_sub_i32 s12, s13, s12
	v_rcp_iflag_f32_e32 v0, v0
	s_abs_i32 s16, s12
	s_xor_b32 s13, s12, s15
	s_ashr_i32 s13, s13, 31
	v_mul_f32_e32 v0, 0x4f7ffffe, v0
	v_cvt_u32_f32_e32 v0, v0
	s_mov_b32 s40, s74
	s_mov_b64 s[36:37], s[56:57]
	v_readfirstlane_b32 s19, v0
	s_mul_i32 s18, s18, s19
	s_mul_hi_u32 s18, s19, s18
	s_add_i32 s19, s19, s18
	s_mul_hi_u32 s18, s16, s19
	s_mul_i32 s19, s18, s17
	s_sub_i32 s16, s16, s19
	s_add_i32 s19, s18, 1
	s_sub_i32 s20, s16, s17
	s_cmp_ge_u32 s16, s17
	s_cselect_b32 s18, s19, s18
	s_cselect_b32 s16, s20, s16
	s_add_i32 s19, s18, 1
	s_cmp_ge_u32 s16, s17
	s_cselect_b32 s16, s19, s18
	s_xor_b32 s16, s16, s13
	s_sub_i32 s75, s16, s13
	s_mul_i32 s13, s75, s15
	s_sub_i32 s12, s12, s13
	s_add_i32 s76, s12, s14
	s_ashr_i32 s12, s76, 31
	s_mul_i32 s12, s10, s12
	s_mul_hi_u32 s13, s10, s76
	s_add_i32 s14, s13, s12
	s_lshr_b64 s[12:13], s[4:5], 23
	s_mul_i32 s13, s12, s76
	s_add_i32 s14, s14, s13
	s_ashr_i32 s13, s75, 31
	s_mul_i32 s13, s10, s13
	s_mul_hi_u32 s16, s10, s75
	s_add_i32 s13, s16, s13
	s_mul_i32 s12, s12, s75
	s_add_i32 s13, s13, s12
	s_mul_i32 s12, s10, s75
	s_add_u32 s22, s56, s12
	s_addc_u32 s23, s57, s13
	s_add_i32 s50, s3, 0
	s_add_i32 m0, s50, 0x10000
	s_mul_i32 s15, s10, s76
	global_load_lds_dwordx4 v112, s[22:23]
	s_add_i32 m0, s50, 0x12000
	s_add_u32 s12, s22, s8
	global_load_lds_dwordx4 v130, s[22:23]
	s_addc_u32 s13, s23, s9
	s_add_i32 m0, s50, 0x14000
	v_lshl_add_u64 v[4:5], s[12:13], 0, v[112:113]
	global_load_lds_dwordx4 v112, s[12:13]
	s_add_i32 m0, s50, 0x16000
	v_lshl_add_u64 v[6:7], s[12:13], 0, v[130:131]
	global_load_lds_dwordx4 v130, s[12:13]
	v_readlane_b32 s12, v252, 4
	v_readlane_b32 s13, v252, 5
	s_add_u32 s20, s12, s15
	s_addc_u32 s21, s13, s14
	s_add_i32 s51, s50, 0x2000
	s_mov_b32 m0, s50
	s_add_u32 s12, s20, s8
	global_load_lds_dwordx4 v112, s[20:21]
	s_mov_b32 m0, s51
	s_addc_u32 s13, s21, s9
	s_add_i32 s54, s50, 0x4000
	global_load_lds_dwordx4 v130, s[20:21]
	s_mov_b32 m0, s54
	s_add_i32 s55, s50, 0x6000
	global_load_lds_dwordx4 v112, s[12:13]
	s_mov_b32 m0, s55
	s_cmp_eq_u32 s7, 1
	global_load_lds_dwordx4 v130, s[12:13]
	v_lshl_add_u64 v[0:1], s[22:23], 0, v[112:113]
	v_lshl_add_u64 v[2:3], s[22:23], 0, v[130:131]
	v_lshl_add_u64 v[8:9], s[20:21], 0, v[112:113]
	v_lshl_add_u64 v[10:11], s[20:21], 0, v[130:131]
	s_cselect_b64 s[12:13], -1, 0
	s_cmp_lg_u32 s7, 1
	s_cbranch_scc1 .LBB0_743
	s_barrier

; __device__ __forceinline__ int tid_opaque() { int t = (int)threadIdx.x; asm volatile("" : "+v"(t)); return t; }
; #define PG8_WAIT_V(n) asm volatile("s_waitcnt vmcnt(" #n ")" ::: "memory")
; #define PG8_BAR __builtin_amdgcn_s_barrier()
; template <class Epi, class Sched, bool ALIGN_EPI = false, bool SP2 = false>
; __device__ __forceinline__ void gemm_phase(PG8_LAS unsigned char* lds, const Gemm g, const Sched& S, const Epi& E) {
;     const int tid = tid_opaque(), wid = __builtin_amdgcn_readfirstlane(tid >> 6), lane = tid & 63, wr = wid >> 2, wc = wid & 3, fr = lane & 15, fq = lane >> 4;
;     const int K = g.K, nt = K / BK;
;     unsigned voffA[2], voffB[2];
; #pragma unroll
;     for (int i = 0; i < 2; ++i) { int R, C; stage_rc(tid * 16 + i * 8192, R, C); const int Rb = Epi::PERM ? ((R & ~31) + perm32(R & 31)) : R;
;         voffA[i] = (unsigned)(R * K + C) * 2u; voffB[i] = (unsigned)(Rb * K + C) * 2u; }
;     const size_t kstep = (size_t)(BK * 2);
;     const size_t hstep = (size_t)HALF * K * 2;
;     const size_t tstep = 2 * hstep;
;     const unsigned ldsw = (unsigned)wid * 1024u;
;     const int aoff = lds_byte(wr * 64 + fr, fq * 8), boff = lds_byte(wc * 32 + fr, fq * 8);
;     ...
;     Unit cur, nxt; int ui = 0;
;     if (!S.next(0, cur)) return;
;     f32x4 acc[2][2][4][2];
; #pragma unroll
;     for (int a = 0; a < 2; ++a)
; #pragma unroll
;         for (int b = 0; b < 2; ++b)
; #pragma unroll
;             for (int m = 0; m < 4; ++m)
; #pragma unroll
;                 for (int n = 0; n < 2; ++n) acc[a][b][m][n] = (f32x4){0.f, 0.f, 0.f, 0.f};
;     bf16x8 At[4][2], B0[2][2], B1[2][2];
;     const char* cA = (const char*)g.A + (size_t)cur.pm * tstep; const char* cB = (const char*)g.Bt + (size_t)cur.pn * tstep;
;     S.a_ready(cur);
;     if constexpr (SP2) {
;         PG8_STAGE(PG8_SB(0, 0), cB, voffB); PG8_STAGE(PG8_SB(0, 1), cB + hstep, voffB); PG8_STAGE(PG8_SA(0, 0), cA, voffA); PG8_STAGE(PG8_SA(0, 1), cA + hstep, voffA);
;         if (wr == 1) PG8_BAR;
;         PG8_WAIT_V(2); PG8_BAR;
;         PG8_STAGE(PG8_SB(1, 0), cB + kstep, voffB); PG8_STAGE(PG8_SA(1, 0), cA + kstep, voffA); PG8_STAGE(PG8_SB(1, 1), cB + hstep + kstep, voffB);
;         PG8_WAIT_V(6); PG8_BAR;
;     } else {
;         PG8_STAGE(PG8_SB(0, 0), cB, voffB); PG8_STAGE(PG8_SA(0, 0), cA, voffA); PG8_STAGE(PG8_SB(0, 1), cB + hstep, voffB); PG8_STAGE(PG8_SA(0, 1), cA + hstep, voffA);
.LBB0_764:
	s_and_b64 vcc, exec, s[54:55]
	s_cbranch_vccz .LBB0_786
	s_movk_i32 s4, 0x400
	s_movk_i32 s0, 0x1600
	s_ashr_i32 s1, s0, 31
	s_lshr_b32 s1, s1, 24
	s_add_i32 s0, s0, s1
	s_ashr_i32 s12, s0, 8
	s_mov_b32 s2, s24
	s_lshl_b32 s0, s12, 6
	v_mov_b32_e32 v12, v154
	s_cmp_ge_i32 s2, s0
	v_readfirstlane_b32 s1, v12
	s_cbranch_scc1 .LBB0_786
	v_lshlrev_b32_e32 v0, 4, v12
	v_add_u32_e32 v1, 0x2000, v0
	v_ashrrev_i32_e32 v2, 31, v1
	v_lshrrev_b32_e32 v2, 22, v2
	v_add_u32_e32 v2, v1, v2
	v_ashrrev_i32_e32 v2, 10, v2
	s_waitcnt lgkmcnt(0)
	v_mul_i32_i24_e32 v3, 0x400, v2
	v_sub_u32_e32 v1, v1, v3
	v_lshrrev_b32_e32 v3, 4, v1
	v_bitop3_b32 v1, v3, v1, 32 bitop3:0x6c
	v_ashrrev_i32_e32 v3, 31, v1
	v_lshrrev_b32_e32 v3, 26, v3
	v_add_u32_e32 v3, v1, v3
	v_lshlrev_b32_e32 v5, 3, v2
	v_ashrrev_i32_e32 v4, 6, v3
	v_and_b32_e32 v5, -16, v5
	v_lshlrev_b32_e32 v2, 5, v2
	v_add_u32_e32 v5, v4, v5
	v_and_b32_e32 v13, 32, v2
	v_and_b32_e32 v2, 0xc0, v3
	v_and_b32_e32 v4, 3, v4
	s_mov_b32 s13, 0x7fffffe0
	v_lshrrev_b32_e32 v6, 2, v5
	v_lshlrev_b32_e32 v7, 1, v5
	v_sub_u32_e32 v1, v1, v2
	v_and_or_b32 v4, v5, s13, v4
	v_and_b32_e32 v6, 4, v6
	v_and_b32_e32 v7, 24, v7
	v_ashrrev_i16_sdwa v1, v183, sext(v1) dst_sel:DWORD dst_unused:UNUSED_PAD src0_sel:DWORD src1_sel:BYTE_0
	v_or3_b32 v4, v4, v6, v7
	v_bfe_i32 v14, v1, 0, 16
	v_mul_lo_u32 v4, v4, s4
	v_add_u32_e32 v1, v13, v14
	v_mul_lo_u32 v15, v5, s4
	v_add_lshl_u32 v130, v4, v1, 1
	v_add_lshl_u32 v132, v1, v15, 1
	v_bfe_i32 v1, v12, 27, 1
	v_lshrrev_b32_e32 v1, 22, v1
	v_add_u32_e32 v1, v0, v1
	v_and_b32_e32 v1, 0xfffffc00, v1
	v_sub_u32_e32 v0, v0, v1
	v_ashrrev_i32_e32 v2, 31, v12
	v_lshrrev_b32_e32 v1, 4, v0
	v_lshrrev_b32_e32 v2, 26, v2
	v_bitop3_b32 v1, v1, v0, 32 bitop3:0x6c
	v_ashrrev_i32_e32 v0, 31, v0
	v_add_u32_e32 v2, v12, v2
	v_lshrrev_b32_e32 v0, 26, v0
	v_ashrrev_i32_e32 v2, 6, v2
	v_add_u32_e32 v0, v1, v0
	v_lshlrev_b32_e32 v3, 3, v2
	v_ashrrev_i32_e32 v0, 6, v0
	v_and_b32_e32 v3, -16, v3
	v_add_u32_e32 v3, v0, v3
	v_and_b32_e32 v4, 3, v0
	s_ashr_i32 s25, s2, 31
	v_and_or_b32 v4, v3, s13, v4
	s_lshr_b32 s13, s25, 29
	s_add_i32 s13, s2, s13
	s_ashr_i32 s6, s1, 6
	s_ashr_i32 s5, s4, 31
	s_lshl_b32 s24, s12, 3
	s_ashr_i32 s14, s13, 3
	s_and_b32 s13, s13, -8
	s_ashr_i32 s7, s1, 8
	s_lshl_b64 s[8:9], s[4:5], 8
	s_lshl_b64 s[10:11], s[4:5], 9
	s_lshl_b32 s3, s6, 10
	s_sub_i32 s13, s2, s13
	s_or_b32 s28, s24, 1
	s_cmp_lt_i32 s13, 0
	v_mul_i32_i24_e32 v0, 64, v0
	s_cselect_b32 s15, s28, s24
	s_abs_i32 s29, s24
	v_sub_u32_e32 v0, v1, v0
	v_cvt_f32_u32_e32 v1, s29
	s_mul_i32 s13, s15, s13
	s_sub_i32 s15, 0, s29
	s_add_i32 s13, s13, s14
	v_rcp_iflag_f32_e32 v1, v1
	s_ashr_i32 s14, s13, 31
	s_bfe_i32 s48, s12, 0x1001c
	s_xor_b32 s12, s14, s48
	v_mul_f32_e32 v1, 0x4f7ffffe, v1
	v_cvt_u32_f32_e32 v1, v1
	s_abs_i32 s14, s13
	v_lshrrev_b32_e32 v5, 2, v3
	v_lshlrev_b32_e32 v6, 1, v3
	v_readfirstlane_b32 s49, v1
	s_mul_i32 s15, s15, s49
	s_mul_hi_u32 s15, s49, s15
	s_add_i32 s49, s49, s15
	s_mul_hi_u32 s15, s14, s49
	s_mul_i32 s16, s15, s29
	s_sub_i32 s14, s14, s16
	s_add_i32 s16, s15, 1
	s_sub_i32 s17, s14, s29
	s_cmp_ge_u32 s14, s29
	s_cselect_b32 s15, s16, s15
	s_cselect_b32 s14, s17, s14
	s_add_i32 s16, s15, 1
	s_cmp_ge_u32 s14, s29
	s_cselect_b32 s14, s16, s15
	s_xor_b32 s14, s14, s12
	s_sub_i32 s12, s14, s12
	s_lshl_b32 s14, s12, 3
	s_sub_i32 s15, 64, s14
	s_min_i32 s15, s15, 8
	s_abs_i32 s16, s15
	v_cvt_f32_u32_e32 v1, s16
	v_and_b32_e32 v5, 4, v5
	v_and_b32_e32 v6, 24, v6
	v_lshlrev_b32_e32 v2, 5, v2
	v_ashrrev_i16_sdwa v0, v183, sext(v0) dst_sel:DWORD dst_unused:UNUSED_PAD src0_sel:DWORD src1_sel:BYTE_0
	v_or3_b32 v4, v4, v5, v6
	v_and_b32_e32 v16, 32, v2
	v_bfe_i32 v17, v0, 0, 16
	v_mul_lo_u32 v4, v4, s4
	v_add_u32_e32 v0, v16, v17
	v_mul_lo_u32 v18, v3, s4
	v_add_lshl_u32 v112, v4, v0, 1
	v_add_lshl_u32 v134, v0, v18, 1
	v_rcp_iflag_f32_e32 v0, v1
	s_sub_i32 s18, 0, s16
	s_mul_i32 s12, s12, s24
	s_sub_i32 s12, s13, s12
	v_mul_f32_e32 v0, 0x4f7ffffe, v0
	v_cvt_u32_f32_e32 v0, v0
	s_abs_i32 s17, s12
	s_xor_b32 s13, s12, s15
	s_ashr_i32 s13, s13, 31
	v_readfirstlane_b32 s19, v0
	s_mul_i32 s18, s18, s19
	s_mul_hi_u32 s18, s19, s18
	s_add_i32 s19, s19, s18
	s_mul_hi_u32 s18, s17, s19
	s_mul_i32 s19, s18, s16
	s_sub_i32 s17, s17, s19
	s_add_i32 s19, s18, 1
	s_sub_i32 s20, s17, s16
	s_cmp_ge_u32 s17, s16
	s_cselect_b32 s18, s19, s18
	s_cselect_b32 s17, s20, s17
	s_add_i32 s19, s18, 1
	s_cmp_ge_u32 s17, s16
	s_cselect_b32 s16, s19, s18
	s_xor_b32 s16, s16, s13
	s_sub_i32 s75, s16, s13
	s_mul_i32 s13, s75, s15
	s_sub_i32 s12, s12, s13
	s_add_i32 s76, s12, s14
	s_ashr_i32 s12, s76, 31
	s_mul_i32 s12, s10, s12
	s_mul_hi_u32 s13, s10, s76
	s_add_i32 s14, s13, s12
	s_lshr_b64 s[12:13], s[4:5], 23
	s_mul_i32 s13, s12, s76
	s_add_i32 s14, s14, s13
	s_ashr_i32 s13, s75, 31
	s_mul_i32 s13, s10, s13
	s_mul_hi_u32 s16, s10, s75
	s_add_i32 s13, s16, s13
	s_mul_i32 s12, s12, s75
	s_add_i32 s13, s13, s12
	s_mul_i32 s12, s10, s75
	s_add_u32 s22, s26, s12
	s_addc_u32 s23, s27, s13
	s_add_i32 s50, s3, 0
	s_add_i32 m0, s50, 0x10000
	s_mul_i32 s15, s10, s76
	global_load_lds_dwordx4 v112, s[22:23]
	s_add_i32 m0, s50, 0x12000
	s_add_u32 s12, s22, s8
	global_load_lds_dwordx4 v130, s[22:23]
	s_addc_u32 s13, s23, s9
	s_add_i32 m0, s50, 0x14000
	v_mov_b32_e32 v131, v113
	global_load_lds_dwordx4 v112, s[12:13]
	s_add_i32 m0, s50, 0x16000
	s_add_u32 s20, s96, s15
	s_addc_u32 s21, s97, s14
	s_add_i32 s51, s50, 0x2000
	global_load_lds_dwordx4 v130, s[12:13]
	s_mov_b32 m0, s50
	s_add_u32 s14, s20, s8
	global_load_lds_dwordx4 v134, s[20:21]
	s_mov_b32 m0, s51
	s_addc_u32 s15, s21, s9
	s_add_i32 s54, s50, 0x4000
	global_load_lds_dwordx4 v132, s[20:21]
	s_mov_b32 m0, s54
	s_add_i32 s55, s50, 0x6000
	global_load_lds_dwordx4 v134, s[14:15]
	s_mov_b32 m0, s55
	v_mov_b32_e32 v135, v113
	global_load_lds_dwordx4 v132, s[14:15]
	v_mov_b32_e32 v133, v113
	s_cmp_eq_u32 s7, 1
	s_mov_b64 s[40:41], s[64:65]
	s_mov_b32 s38, s74
	s_mov_b64 s[36:37], s[56:57]
	v_lshl_add_u64 v[8:9], s[22:23], 0, v[112:113]
	v_lshl_add_u64 v[4:5], s[22:23], 0, v[130:131]
	v_lshl_add_u64 v[2:3], s[12:13], 0, v[112:113]
	v_lshl_add_u64 v[0:1], s[12:13], 0, v[130:131]
	v_lshl_add_u64 v[6:7], s[20:21], 0, v[134:135]
	s_cselect_b64 s[12:13], -1, 0
	s_cmp_lg_u32 s7, 1
	v_lshl_add_u64 v[10:11], s[20:21], 0, v[132:133]
	s_cbranch_scc1 .LBB0_768
	s_barrier

; __device__ __forceinline__ int tid_opaque() { int t = (int)threadIdx.x; asm volatile("" : "+v"(t)); return t; }
; __device__ __forceinline__ int bid_opaque() { int t = (int)blockIdx.x; asm volatile("" : "+s"(t)); return t; }
; __device__ __forceinline__ void cvt_tile(unsigned char* lds, const float* src, int ld, int n_begin, int K, bf16_t* dst, int Kd, int koff, int mode, int roff, int t, int tid) {
;     const int ntk = Kd / 64; unsigned short* tile = (unsigned short*)lds;
;     const int tn = t / ntk, tk = t - tn * ntk; const int n0 = tn * 64, k0 = tk * 64;
;     const bool valid = (src != nullptr) && (k0 >= koff) && (k0 < koff + K);
;     __syncthreads();
;     if (valid) {
; #pragma unroll
;         for (int it = 0; it < 2; ++it) { const int idx = tid + 512 * it, kr = idx >> 4, nc4 = idx & 15;
;             const f32x4 v = *(const f32x4*)(src + (size_t)(k0 - koff + kr) * ld + n_begin + n0 + 4 * nc4);
; #pragma unroll
;             for (int j = 0; j < 4; ++j) tile[(4 * nc4 + j) * 66 + kr] = f2bf(v[j]); }
;     }
;     __syncthreads();
;     { const int n = tid >> 3, kc = (tid & 7) * 8; u32x4 w = (u32x4){0u, 0u, 0u, 0u};
;       if (valid) { const unsigned* tp = (const unsigned*)(tile + n * 66 + kc); w.x = tp[0]; w.y = tp[1]; w.z = tp[2]; w.w = tp[3]; }
;       const int nl = n0 + n; const int drow = (mode == 0) ? (nl + roff) : (256 * (nl >> 7) + (nl & 127) + roff);
;       *(u32x4*)(dst + (size_t)drow * Kd + k0 + kc) = w; }
; }
; __device__ __forceinline__ void cvt_job(unsigned char* lds, const float* src, int ld, int n_begin, int n_count, int K, bf16_t* dst, int Kd, int koff, int mode, int roff, int& cum) {
;     const int tid = tid_opaque(), G = gridDim.x; const int bid = bid_opaque();
;     const int ntiles = (n_count / 64) * (Kd / 64);
;     const int start = (int)(((unsigned)bid + (unsigned)G - (unsigned)(cum % G)) % (unsigned)G);
;     for (int t = start; t < ntiles; t += G) cvt_tile(lds, src, ld, n_begin, K, dst, Kd, koff, mode, roff, t, tid);
; __device__ void cvt_ffn(unsigned char* lds, unsigned char* ws, const float* w_in, const float* w_out) {
;     int cum = 0; bf16_t* WA = (bf16_t*)(ws + WS_WA); bf16_t* WB = (bf16_t*)(ws + WS_WB);
;     cvt_job(lds, w_in, NFF, 0, DFF, DM, WA, DM, 0, 1, 0, cum);
;     cvt_job(lds, w_in, NFF, DFF, DFF, DM, WA, DM, 0, 1, 128, cum);
.LBB0_786:
	s_andn2_b64 vcc, exec, s[42:43]
	s_cbranch_vccnz .LBB0_815
	s_cmp_lg_u32 s75, 0
	s_cbranch_scc1 .LBB0_815
	v_readlane_b32 s0, v253, 16
	v_readlane_b32 s2, v253, 18
	v_readlane_b32 s1, v253, 17
	v_readlane_b32 s4, v253, 20
	v_readlane_b32 s0, v255, 0
	v_mov_b32_e32 v0, v154
	s_mov_b32 s2, s24
	v_readlane_b32 s3, v253, 19
	v_readlane_b32 s5, v253, 21
	s_add_u32 s0, s4, s0
	v_readlane_b32 s1, v254, 63
	s_addc_u32 s1, s5, s1
	s_add_i32 s2, s2, s94
	v_readlane_b32 s3, v254, 10
	s_mul_hi_u32 s3, s2, s3
	s_mul_i32 s3, s3, s94
	s_sub_i32 s2, s2, s3
	s_sub_i32 s3, s2, s94
	s_cmp_ge_u32 s2, s94
	s_cselect_b32 s2, s3, s2
	s_sub_i32 s3, s2, s94
	s_cmp_ge_u32 s2, s94
	s_cselect_b32 s2, s3, s2
	s_cmpk_gt_i32 s2, 0x2bf
	v_readlane_b32 s6, v253, 22
	v_readlane_b32 s7, v253, 23
	v_readlane_b32 s8, v253, 24
	v_readlane_b32 s9, v253, 25
	v_readlane_b32 s10, v253, 26
	v_readlane_b32 s11, v253, 27
	v_readlane_b32 s12, v253, 28
	v_readlane_b32 s13, v253, 29
	v_readlane_b32 s14, v253, 30
	v_readlane_b32 s15, v253, 31
	s_cbranch_scc1 .LBB0_795
	v_lshlrev_b32_e32 v1, 2, v0
	v_ashrrev_i32_e32 v6, 4, v0
	s_waitcnt lgkmcnt(0)
	v_add_u32_e32 v3, 0x200, v0
	v_ashrrev_i32_e32 v8, 3, v0
	v_lshlrev_b32_e32 v0, 3, v0
	v_and_b32_e32 v1, 60, v1
	v_ashrrev_i32_e32 v7, 4, v3
	v_and_b32_e32 v0, 56, v0
	s_movk_i32 s3, 0x84
	v_lshlrev_b32_e32 v112, 2, v1
	v_lshl_add_u32 v2, v6, 1, 0
	v_mul_u32_u24_e32 v1, 0x84, v1
	v_lshl_add_u32 v3, v7, 1, 0
	v_mul_lo_u32 v9, v8, s3
	v_lshlrev_b32_e32 v10, 1, v0
	v_lshl_add_u64 v[4:5], s[0:1], 0, v[112:113]
	v_add3_u32 v9, 0, v9, v10
	s_lshl_b32 s3, s2, 6
	v_add_u32_e32 v10, v2, v1
	v_add_u32_e32 v11, v3, v1
	v_lshlrev_b32_e32 v112, 1, v0
	s_branch .LBB0_791
